# gemm8 k-loop: one lgkmcnt wait per two MFMA groups (8 fewer waits per k-tile)
# speedup vs baseline: 1.0140x; 1.0028x over previous
; #define MFMA16(a, b, c) __builtin_amdgcn_mfma_f32_16x16x32_bf16((a), (b), (c), 0, 0, 0)
; template <class Epi>
; DI void gemm8_tile(const bf16_t* __restrict__ Ab, int lda, const bf16_t* __restrict__ Bb, int ldb, int K, int brow, int bcol, const Epi epi,
;                    bool staged, bool has_next, const bf16_t* __restrict__ Abn, const bf16_t* __restrict__ Bbn) {
;     ...
;   for (int t = 0; t < nt; ++t) {
;     const int cur = t & 1;
;     const unsigned char* sa = smem + cur * G8_STAGE_B;
;     const unsigned char* sb = sa + G8_TILE_B;
; #pragma unroll
;     for (int ks = 0; ks < 2; ++ks) {
;       bf16x8 At[8], Bf[4];
;       Bf[0] = *(const bf16x8*)(sb + lds_byte2(wc * 64 + fr, ks * 32 + fq * 8));
;       At[0] = *(const bf16x8*)(sa + lds_byte2(wr * 128 + fr, ks * 32 + fq * 8));
; #pragma unroll
;       for (int n = 1; n < 4; ++n) Bf[n] = *(const bf16x8*)(sb + lds_byte2(wc * 64 + n * 16 + fr, ks * 32 + fq * 8));
; #pragma unroll
;       for (int m = 1; m < 8; ++m) At[m] = *(const bf16x8*)(sa + lds_byte2(wr * 128 + m * 16 + fr, ks * 32 + fq * 8));
;       {
;         __builtin_amdgcn_sched_barrier(0);
;         if (t + 1 < nt) { G8_STAGE_R(cur ^ 1, Ab + (t + 1) * 64, Bb + (t + 1) * 64, 2 * ks, 2 * ks + 2); }
;         else if (has_next) { G8_STAGE_R(0, Abn, Bbn, 2 * ks, 2 * ks + 2); }
;         __builtin_amdgcn_sched_barrier(0);
;       }
; #pragma unroll
;       for (int m = 0; m < 8; ++m)
; #pragma unroll
;         for (int n = 0; n < 4; ++n) acc[m][n] = MFMA16(At[m], Bf[n], acc[m][n]);
;       __builtin_amdgcn_sched_barrier(0);
;     }
;     asm volatile("s_waitcnt vmcnt(0)" ::: "memory");
;     __syncthreads();
.LBB0_462:
	s_and_b32 s15, s14, 0x10000
	s_xor_b32 s56, s15, 0x10000
	v_add_u32_e32 v244, s56, v157
	s_nop 0
	v_readfirstlane_b32 s15, v244
	s_waitcnt lgkmcnt(8)
	v_mfma_f32_16x16x32_bf16 v[126:129], v[184:187], v[168:171], v[126:129]
	v_mfma_f32_16x16x32_bf16 v[122:125], v[184:187], v[172:175], v[122:125]
	s_mov_b32 m0, s15
	v_lshl_add_u64 v[160:161], v[144:145], 0, s[0:1]
	global_load_lds_dwordx4 v[160:161], off
	v_mfma_f32_16x16x32_bf16 v[110:113], v[188:191], v[168:171], v[110:113]
	v_mfma_f32_16x16x32_bf16 v[106:109], v[188:191], v[172:175], v[106:109]
	s_add_u32 m0, s15, 0x8000
	v_lshl_add_u64 v[160:161], v[136:137], 0, s[0:1]
	global_load_lds_dwordx4 v[160:161], off
	s_waitcnt lgkmcnt(6)
	v_mfma_f32_16x16x32_bf16 v[94:97], v[192:195], v[168:171], v[94:97]
	v_mfma_f32_16x16x32_bf16 v[90:93], v[192:195], v[172:175], v[90:93]
	s_add_u32 m0, s15, 0x2000
	v_lshl_add_u64 v[160:161], v[142:143], 0, s[0:1]
	global_load_lds_dwordx4 v[160:161], off
	v_mfma_f32_16x16x32_bf16 v[78:81], v[196:199], v[168:171], v[78:81]
	v_mfma_f32_16x16x32_bf16 v[74:77], v[196:199], v[172:175], v[74:77]
	s_add_u32 m0, s15, 0xa000
	v_lshl_add_u64 v[160:161], v[134:135], 0, s[0:1]
	global_load_lds_dwordx4 v[160:161], off
	s_waitcnt lgkmcnt(4)
	v_mfma_f32_16x16x32_bf16 v[62:65], v[200:203], v[168:171], v[62:65]
	v_mfma_f32_16x16x32_bf16 v[58:61], v[200:203], v[172:175], v[58:61]
	s_add_u32 m0, s15, 0x4000
	v_lshl_add_u64 v[160:161], v[140:141], 0, s[0:1]
	global_load_lds_dwordx4 v[160:161], off
	v_mfma_f32_16x16x32_bf16 v[46:49], v[204:207], v[168:171], v[46:49]
	v_mfma_f32_16x16x32_bf16 v[42:45], v[204:207], v[172:175], v[42:45]
	s_add_u32 m0, s15, 0xc000
	v_lshl_add_u64 v[160:161], v[132:133], 0, s[0:1]
	global_load_lds_dwordx4 v[160:161], off
	s_waitcnt lgkmcnt(2)
	v_mfma_f32_16x16x32_bf16 v[30:33], v[232:235], v[168:171], v[30:33]
	v_mfma_f32_16x16x32_bf16 v[26:29], v[232:235], v[172:175], v[26:29]
	s_add_u32 m0, s15, 0x6000
	v_lshl_add_u64 v[160:161], v[138:139], 0, s[0:1]
	global_load_lds_dwordx4 v[160:161], off
	v_mfma_f32_16x16x32_bf16 v[14:17], v[236:239], v[168:171], v[14:17]
	v_mfma_f32_16x16x32_bf16 v[10:13], v[236:239], v[172:175], v[10:13]
	s_add_u32 m0, s15, 0xe000
	v_lshl_add_u64 v[160:161], v[130:131], 0, s[0:1]
	global_load_lds_dwordx4 v[160:161], off
	ds_read_b128 v[168:171], v0 offset:33792
	ds_read_b128 v[172:175], v0 offset:35840
	s_waitcnt lgkmcnt(2)
	v_mfma_f32_16x16x32_bf16 v[118:121], v[184:187], v[176:179], v[118:121]
	v_mfma_f32_16x16x32_bf16 v[114:117], v[184:187], v[180:183], v[114:117]
	ds_read_b128 v[184:187], v159 offset:1024
	v_mfma_f32_16x16x32_bf16 v[102:105], v[188:191], v[176:179], v[102:105]
	v_mfma_f32_16x16x32_bf16 v[98:101], v[188:191], v[180:183], v[98:101]
	ds_read_b128 v[188:191], v208 offset:1024
	v_mfma_f32_16x16x32_bf16 v[86:89], v[192:195], v[176:179], v[86:89]
	v_mfma_f32_16x16x32_bf16 v[82:85], v[192:195], v[180:183], v[82:85]
	ds_read_b128 v[192:195], v209 offset:1024
	v_mfma_f32_16x16x32_bf16 v[70:73], v[196:199], v[176:179], v[70:73]
	v_mfma_f32_16x16x32_bf16 v[66:69], v[196:199], v[180:183], v[66:69]
	ds_read_b128 v[196:199], v231 offset:1024
	v_mfma_f32_16x16x32_bf16 v[54:57], v[200:203], v[176:179], v[54:57]
	v_mfma_f32_16x16x32_bf16 v[50:53], v[200:203], v[180:183], v[50:53]
	ds_read_b128 v[200:203], v240 offset:1024
	v_mfma_f32_16x16x32_bf16 v[38:41], v[204:207], v[176:179], v[38:41]
	v_mfma_f32_16x16x32_bf16 v[34:37], v[204:207], v[180:183], v[34:37]
	ds_read_b128 v[204:207], v241 offset:1024
	v_mfma_f32_16x16x32_bf16 v[22:25], v[232:235], v[176:179], v[22:25]
	v_mfma_f32_16x16x32_bf16 v[18:21], v[232:235], v[180:183], v[18:21]
	ds_read_b128 v[232:235], v242 offset:1024
	v_mfma_f32_16x16x32_bf16 v[6:9], v[236:239], v[176:179], v[6:9]
	v_mfma_f32_16x16x32_bf16 v[2:5], v[236:239], v[180:183], v[2:5]
	ds_read_b128 v[236:239], v243 offset:1024
	ds_read_b128 v[176:179], v0 offset:37888
	ds_read_b128 v[180:183], v0 offset:39936
	s_waitcnt lgkmcnt(8)
	v_mfma_f32_16x16x32_bf16 v[126:129], v[184:187], v[168:171], v[126:129]
	v_mfma_f32_16x16x32_bf16 v[122:125], v[184:187], v[172:175], v[122:125]
	v_add3_u32 v0, s56, v152, v151
	v_mfma_f32_16x16x32_bf16 v[110:113], v[188:191], v[168:171], v[110:113]
	v_mfma_f32_16x16x32_bf16 v[106:109], v[188:191], v[172:175], v[106:109]
	v_add3_u32 v159, s56, v152, v153
	s_waitcnt lgkmcnt(6)
	v_mfma_f32_16x16x32_bf16 v[94:97], v[192:195], v[168:171], v[94:97]
	v_mfma_f32_16x16x32_bf16 v[90:93], v[192:195], v[172:175], v[90:93]
	v_add3_u32 v209, s56, v158, v167
	v_mfma_f32_16x16x32_bf16 v[78:81], v[196:199], v[168:171], v[78:81]
	v_mfma_f32_16x16x32_bf16 v[74:77], v[196:199], v[172:175], v[74:77]
	v_add3_u32 v240, s56, v158, v165
	s_waitcnt lgkmcnt(4)
	v_mfma_f32_16x16x32_bf16 v[62:65], v[200:203], v[168:171], v[62:65]
	v_mfma_f32_16x16x32_bf16 v[58:61], v[200:203], v[172:175], v[58:61]
	v_add3_u32 v242, s56, v158, v163
	v_mfma_f32_16x16x32_bf16 v[46:49], v[204:207], v[168:171], v[46:49]
	v_mfma_f32_16x16x32_bf16 v[42:45], v[204:207], v[172:175], v[42:45]
	v_add3_u32 v208, s56, v158, v150
	s_waitcnt lgkmcnt(2)
	v_mfma_f32_16x16x32_bf16 v[30:33], v[232:235], v[168:171], v[30:33]
	v_mfma_f32_16x16x32_bf16 v[26:29], v[232:235], v[172:175], v[26:29]
	v_add3_u32 v231, s56, v158, v166
	v_mfma_f32_16x16x32_bf16 v[14:17], v[236:239], v[168:171], v[14:17]
	v_mfma_f32_16x16x32_bf16 v[10:13], v[236:239], v[172:175], v[10:13]
	v_add3_u32 v241, s56, v158, v164
	v_add3_u32 v243, s56, v158, v162
	s_waitcnt vmcnt(0) lgkmcnt(0)
	s_barrier
; #define MFMA16(a, b, c) __builtin_amdgcn_mfma_f32_16x16x32_bf16((a), (b), (c), 0, 0, 0)
; template <class Epi>
; DI void gemm8_tile(const bf16_t* __restrict__ Ab, int lda, const bf16_t* __restrict__ Bb, int ldb, int K, int brow, int bcol, const Epi epi,
;                    bool staged, bool has_next, const bf16_t* __restrict__ Abn, const bf16_t* __restrict__ Bbn) {
;     ...
;   for (int t = 0; t < nt; ++t) {
;     const int cur = t & 1;
;     const unsigned char* sa = smem + cur * G8_STAGE_B;
;     const unsigned char* sb = sa + G8_TILE_B;
; #pragma unroll
;     for (int ks = 0; ks < 2; ++ks) {
;       bf16x8 At[8], Bf[4];
;       Bf[0] = *(const bf16x8*)(sb + lds_byte2(wc * 64 + fr, ks * 32 + fq * 8));
;       At[0] = *(const bf16x8*)(sa + lds_byte2(wr * 128 + fr, ks * 32 + fq * 8));
; #pragma unroll
;       for (int n = 1; n < 4; ++n) Bf[n] = *(const bf16x8*)(sb + lds_byte2(wc * 64 + n * 16 + fr, ks * 32 + fq * 8));
; #pragma unroll
;       for (int m = 1; m < 8; ++m) At[m] = *(const bf16x8*)(sa + lds_byte2(wr * 128 + m * 16 + fr, ks * 32 + fq * 8));
;       {
;         __builtin_amdgcn_sched_barrier(0);
;         if (t + 1 < nt) { G8_STAGE_R(cur ^ 1, Ab + (t + 1) * 64, Bb + (t + 1) * 64, 2 * ks, 2 * ks + 2); }
;         else if (has_next) { G8_STAGE_R(0, Abn, Bbn, 2 * ks, 2 * ks + 2); }
;         __builtin_amdgcn_sched_barrier(0);
;       }
; #pragma unroll
;       for (int m = 0; m < 8; ++m)
; #pragma unroll
;         for (int n = 0; n < 4; ++n) acc[m][n] = MFMA16(At[m], Bf[n], acc[m][n]);
;       __builtin_amdgcn_sched_barrier(0);
;     }
;     asm volatile("s_waitcnt vmcnt(0)" ::: "memory");
;     __syncthreads();
;   }
	ds_read_b128 v[168:171], v0 offset:32768
	ds_read_b128 v[172:175], v0 offset:34816
	v_mfma_f32_16x16x32_bf16 v[118:121], v[184:187], v[176:179], v[118:121]
	v_mfma_f32_16x16x32_bf16 v[114:117], v[184:187], v[180:183], v[114:117]
	ds_read_b128 v[184:187], v159
	v_mfma_f32_16x16x32_bf16 v[102:105], v[188:191], v[176:179], v[102:105]
	v_mfma_f32_16x16x32_bf16 v[98:101], v[188:191], v[180:183], v[98:101]
	ds_read_b128 v[188:191], v208
	v_mfma_f32_16x16x32_bf16 v[86:89], v[192:195], v[176:179], v[86:89]
	v_mfma_f32_16x16x32_bf16 v[82:85], v[192:195], v[180:183], v[82:85]
	ds_read_b128 v[192:195], v209
	v_mfma_f32_16x16x32_bf16 v[70:73], v[196:199], v[176:179], v[70:73]
	v_mfma_f32_16x16x32_bf16 v[66:69], v[196:199], v[180:183], v[66:69]
	ds_read_b128 v[196:199], v231
	v_mfma_f32_16x16x32_bf16 v[54:57], v[200:203], v[176:179], v[54:57]
	v_mfma_f32_16x16x32_bf16 v[50:53], v[200:203], v[180:183], v[50:53]
	ds_read_b128 v[200:203], v240
	v_mfma_f32_16x16x32_bf16 v[38:41], v[204:207], v[176:179], v[38:41]
	v_mfma_f32_16x16x32_bf16 v[34:37], v[204:207], v[180:183], v[34:37]
	ds_read_b128 v[204:207], v241
	v_mfma_f32_16x16x32_bf16 v[22:25], v[232:235], v[176:179], v[22:25]
	v_mfma_f32_16x16x32_bf16 v[18:21], v[232:235], v[180:183], v[18:21]
	ds_read_b128 v[232:235], v242
	v_mfma_f32_16x16x32_bf16 v[6:9], v[236:239], v[176:179], v[6:9]
	v_mfma_f32_16x16x32_bf16 v[2:5], v[236:239], v[180:183], v[2:5]
	ds_read_b128 v[236:239], v243
	ds_read_b128 v[176:179], v0 offset:36864
	ds_read_b128 v[180:183], v0 offset:38912
	s_add_u32 s0, s0, 0x80
	s_addc_u32 s1, s1, 0
	s_add_i32 s14, s14, 0x10000
	s_cmpk_eq_i32 s0, 0x780
	s_cbranch_scc0 .LBB0_462
	s_waitcnt lgkmcnt(0)
	s_add_i32 s0, 0, 0x18000
	v_add_u32_e32 v0, s0, v152
	v_add_u32_e32 v0, v0, v151
	v_add_u32_e32 v130, s30, v152
	v_add_u32_e32 v206, v130, v153
	ds_read_b128 v[130:133], v0
	ds_read_b128 v[134:137], v0 offset:2048
	ds_read_b128 v[138:141], v0 offset:4096
	ds_read_b128 v[142:145], v0 offset:6144
	v_add_u32_e32 v170, s30, v158
	v_add_u32_e32 v208, v170, v167
	v_add_u32_e32 v231, v170, v165
	v_add_u32_e32 v233, v170, v163
	v_add_u32_e32 v207, v170, v150
	ds_read_b128 v[150:153], v206
	ds_read_b128 v[158:161], v207
	v_add_u32_e32 v209, v170, v166
	ds_read_b128 v[166:169], v208
	ds_read_b128 v[174:177], v209
	v_add_u32_e32 v232, v170, v164
	ds_read_b128 v[182:185], v231
	ds_read_b128 v[190:193], v232
	v_add_u32_e32 v234, v170, v162
	ds_read_b128 v[198:201], v233
	ds_read_b128 v[202:205], v234
	v_cndmask_b32_e64 v162, 0, 1, s[54:55]
	v_cmp_ne_u32_e64 s[0:1], 1, v162
	s_andn2_b64 vcc, exec, s[54:55]
	s_cbranch_vccnz .LBB0_465
	v_readfirstlane_b32 s14, v157
	v_lshl_add_u64 v[162:163], s[10:11], 0, v[148:149]
	s_mov_b32 m0, s14
	v_readfirstlane_b32 s14, v156
	v_lshl_add_u64 v[148:149], s[38:39], 0, v[148:149]
	global_load_lds_dwordx4 v[162:163], off
	s_mov_b32 m0, s14
	v_readfirstlane_b32 s14, v155
	v_lshl_add_u64 v[164:165], s[10:11], 0, v[146:147]
	global_load_lds_dwordx4 v[148:149], off
	s_mov_b32 m0, s14
	v_readfirstlane_b32 s14, v154
	v_lshl_add_u64 v[146:147], s[38:39], 0, v[146:147]
	global_load_lds_dwordx4 v[164:165], off
	s_mov_b32 m0, s14
	s_nop 0
	global_load_lds_dwordx4 v[146:147], off

; #define MFMA16(a, b, c) __builtin_amdgcn_mfma_f32_16x16x32_bf16((a), (b), (c), 0, 0, 0)
; template <class Epi>
; DI void gemm8_tile(const bf16_t* __restrict__ Ab, int lda, const bf16_t* __restrict__ Bb, int ldb, int K, int brow, int bcol, const Epi epi,
;                    bool staged, bool has_next, const bf16_t* __restrict__ Abn, const bf16_t* __restrict__ Bbn) {
;     ...
;   for (int t = 0; t < nt; ++t) {
;     const int cur = t & 1;
;     const unsigned char* sa = smem + cur * G8_STAGE_B;
;     const unsigned char* sb = sa + G8_TILE_B;
; #pragma unroll
;     for (int ks = 0; ks < 2; ++ks) {
;       bf16x8 At[8], Bf[4];
;       Bf[0] = *(const bf16x8*)(sb + lds_byte2(wc * 64 + fr, ks * 32 + fq * 8));
;       At[0] = *(const bf16x8*)(sa + lds_byte2(wr * 128 + fr, ks * 32 + fq * 8));
; #pragma unroll
;       for (int n = 1; n < 4; ++n) Bf[n] = *(const bf16x8*)(sb + lds_byte2(wc * 64 + n * 16 + fr, ks * 32 + fq * 8));
; #pragma unroll
;       for (int m = 1; m < 8; ++m) At[m] = *(const bf16x8*)(sa + lds_byte2(wr * 128 + m * 16 + fr, ks * 32 + fq * 8));
;       {
;         __builtin_amdgcn_sched_barrier(0);
;         if (t + 1 < nt) { G8_STAGE_R(cur ^ 1, Ab + (t + 1) * 64, Bb + (t + 1) * 64, 2 * ks, 2 * ks + 2); }
;         else if (has_next) { G8_STAGE_R(0, Abn, Bbn, 2 * ks, 2 * ks + 2); }
;         __builtin_amdgcn_sched_barrier(0);
;       }
; #pragma unroll
;       for (int m = 0; m < 8; ++m)
; #pragma unroll
;         for (int n = 0; n < 4; ++n) acc[m][n] = MFMA16(At[m], Bf[n], acc[m][n]);
;       __builtin_amdgcn_sched_barrier(0);
;     }
;     asm volatile("s_waitcnt vmcnt(0)" ::: "memory");
;     __syncthreads();
.LBB0_483:
	s_and_b32 s57, s56, 0x10000
	s_xor_b32 s58, s57, 0x10000
	v_add_u32_e32 v244, s58, v185
	s_nop 0
	v_readfirstlane_b32 s57, v244
	s_waitcnt lgkmcnt(8)
	v_mfma_f32_16x16x32_bf16 v[126:129], v[174:177], v[158:161], v[126:129]
	v_mfma_f32_16x16x32_bf16 v[122:125], v[174:177], v[162:165], v[122:125]
	s_mov_b32 m0, s57
	v_lshl_add_u64 v[208:209], v[130:131], 0, s[0:1]
	global_load_lds_dwordx4 v[208:209], off
	v_mfma_f32_16x16x32_bf16 v[110:113], v[186:189], v[158:161], v[110:113]
	v_mfma_f32_16x16x32_bf16 v[106:109], v[186:189], v[162:165], v[106:109]
	s_add_u32 m0, s57, 0x8000
	v_lshl_add_u64 v[208:209], v[138:139], 0, s[0:1]
	global_load_lds_dwordx4 v[208:209], off
	s_waitcnt lgkmcnt(6)
	v_mfma_f32_16x16x32_bf16 v[94:97], v[190:193], v[158:161], v[94:97]
	v_mfma_f32_16x16x32_bf16 v[90:93], v[190:193], v[162:165], v[90:93]
	s_add_u32 m0, s57, 0x2000
	v_lshl_add_u64 v[208:209], v[132:133], 0, s[0:1]
	global_load_lds_dwordx4 v[208:209], off
	v_mfma_f32_16x16x32_bf16 v[78:81], v[212:215], v[158:161], v[78:81]
	v_mfma_f32_16x16x32_bf16 v[74:77], v[212:215], v[162:165], v[74:77]
	s_add_u32 m0, s57, 0xa000
	v_lshl_add_u64 v[208:209], v[140:141], 0, s[0:1]
	global_load_lds_dwordx4 v[208:209], off
	s_waitcnt lgkmcnt(4)
	v_mfma_f32_16x16x32_bf16 v[62:65], v[222:225], v[158:161], v[62:65]
	v_mfma_f32_16x16x32_bf16 v[58:61], v[222:225], v[162:165], v[58:61]
	s_add_u32 m0, s57, 0x4000
	v_lshl_add_u64 v[208:209], v[134:135], 0, s[0:1]
	global_load_lds_dwordx4 v[208:209], off
	v_mfma_f32_16x16x32_bf16 v[46:49], v[226:229], v[158:161], v[46:49]
	v_mfma_f32_16x16x32_bf16 v[42:45], v[226:229], v[162:165], v[42:45]
	s_add_u32 m0, s57, 0xc000
	v_lshl_add_u64 v[208:209], v[142:143], 0, s[0:1]
	global_load_lds_dwordx4 v[208:209], off
	s_waitcnt lgkmcnt(2)
	v_mfma_f32_16x16x32_bf16 v[30:33], v[230:233], v[158:161], v[30:33]
	v_mfma_f32_16x16x32_bf16 v[26:29], v[230:233], v[162:165], v[26:29]
	s_add_u32 m0, s57, 0x6000
	v_lshl_add_u64 v[208:209], v[136:137], 0, s[0:1]
	global_load_lds_dwordx4 v[208:209], off
	v_mfma_f32_16x16x32_bf16 v[14:17], v[234:237], v[158:161], v[14:17]
	v_mfma_f32_16x16x32_bf16 v[10:13], v[234:237], v[162:165], v[10:13]
	s_add_u32 m0, s57, 0xe000
	v_lshl_add_u64 v[208:209], v[144:145], 0, s[0:1]
	global_load_lds_dwordx4 v[208:209], off
	ds_read_b128 v[158:161], v0 offset:33792
	ds_read_b128 v[162:165], v0 offset:35840
	s_waitcnt lgkmcnt(2)
	v_mfma_f32_16x16x32_bf16 v[118:121], v[174:177], v[166:169], v[118:121]
	v_mfma_f32_16x16x32_bf16 v[114:117], v[174:177], v[170:173], v[114:117]
	ds_read_b128 v[174:177], v157 offset:1024
	v_mfma_f32_16x16x32_bf16 v[102:105], v[186:189], v[166:169], v[102:105]
	v_mfma_f32_16x16x32_bf16 v[98:101], v[186:189], v[170:173], v[98:101]
	ds_read_b128 v[186:189], v207 offset:1024
	v_mfma_f32_16x16x32_bf16 v[86:89], v[190:193], v[166:169], v[86:89]
	v_mfma_f32_16x16x32_bf16 v[82:85], v[190:193], v[170:173], v[82:85]
	ds_read_b128 v[190:193], v238 offset:1024
	v_mfma_f32_16x16x32_bf16 v[70:73], v[212:215], v[166:169], v[70:73]
	v_mfma_f32_16x16x32_bf16 v[66:69], v[212:215], v[170:173], v[66:69]
	ds_read_b128 v[212:215], v239 offset:1024
	v_mfma_f32_16x16x32_bf16 v[54:57], v[222:225], v[166:169], v[54:57]
	v_mfma_f32_16x16x32_bf16 v[50:53], v[222:225], v[170:173], v[50:53]
	ds_read_b128 v[222:225], v240 offset:1024
	v_mfma_f32_16x16x32_bf16 v[38:41], v[226:229], v[166:169], v[38:41]
	v_mfma_f32_16x16x32_bf16 v[34:37], v[226:229], v[170:173], v[34:37]
	ds_read_b128 v[226:229], v241 offset:1024
	v_mfma_f32_16x16x32_bf16 v[22:25], v[230:233], v[166:169], v[22:25]
	v_mfma_f32_16x16x32_bf16 v[18:21], v[230:233], v[170:173], v[18:21]
	ds_read_b128 v[230:233], v242 offset:1024
	v_mfma_f32_16x16x32_bf16 v[6:9], v[234:237], v[166:169], v[6:9]
	v_mfma_f32_16x16x32_bf16 v[2:5], v[234:237], v[170:173], v[2:5]
	ds_read_b128 v[234:237], v243 offset:1024
	ds_read_b128 v[166:169], v0 offset:37888
	ds_read_b128 v[170:173], v0 offset:39936
	s_waitcnt lgkmcnt(8)
	v_mfma_f32_16x16x32_bf16 v[126:129], v[174:177], v[158:161], v[126:129]
	v_mfma_f32_16x16x32_bf16 v[122:125], v[174:177], v[162:165], v[122:125]
	v_add3_u32 v0, s58, v155, v153
	v_mfma_f32_16x16x32_bf16 v[110:113], v[186:189], v[158:161], v[110:113]
	v_mfma_f32_16x16x32_bf16 v[106:109], v[186:189], v[162:165], v[106:109]
	v_add3_u32 v157, s58, v155, v156
	s_waitcnt lgkmcnt(6)
	v_mfma_f32_16x16x32_bf16 v[94:97], v[190:193], v[158:161], v[94:97]
	v_mfma_f32_16x16x32_bf16 v[90:93], v[190:193], v[162:165], v[90:93]
	v_add3_u32 v238, s58, v154, v152
	v_mfma_f32_16x16x32_bf16 v[78:81], v[212:215], v[158:161], v[78:81]
	v_mfma_f32_16x16x32_bf16 v[74:77], v[212:215], v[162:165], v[74:77]
	v_add3_u32 v240, s58, v154, v149
	s_waitcnt lgkmcnt(4)
	v_mfma_f32_16x16x32_bf16 v[62:65], v[222:225], v[158:161], v[62:65]
	v_mfma_f32_16x16x32_bf16 v[58:61], v[222:225], v[162:165], v[58:61]
	v_add3_u32 v242, s58, v154, v147
	v_mfma_f32_16x16x32_bf16 v[46:49], v[226:229], v[158:161], v[46:49]
	v_mfma_f32_16x16x32_bf16 v[42:45], v[226:229], v[162:165], v[42:45]
	v_add3_u32 v207, s58, v154, v150
	s_waitcnt lgkmcnt(2)
	v_mfma_f32_16x16x32_bf16 v[30:33], v[230:233], v[158:161], v[30:33]
	v_mfma_f32_16x16x32_bf16 v[26:29], v[230:233], v[162:165], v[26:29]
	v_add3_u32 v239, s58, v154, v151
	v_mfma_f32_16x16x32_bf16 v[14:17], v[234:237], v[158:161], v[14:17]
	v_mfma_f32_16x16x32_bf16 v[10:13], v[234:237], v[162:165], v[10:13]
	v_add3_u32 v241, s58, v154, v148
	v_add3_u32 v243, s58, v154, v146
	s_waitcnt vmcnt(0) lgkmcnt(0)
	s_barrier
; #define MFMA16(a, b, c) __builtin_amdgcn_mfma_f32_16x16x32_bf16((a), (b), (c), 0, 0, 0)
; template <class Epi>
; DI void gemm8_tile(const bf16_t* __restrict__ Ab, int lda, const bf16_t* __restrict__ Bb, int ldb, int K, int brow, int bcol, const Epi epi,
;                    bool staged, bool has_next, const bf16_t* __restrict__ Abn, const bf16_t* __restrict__ Bbn) {
;     ...
;   for (int t = 0; t < nt; ++t) {
;     const int cur = t & 1;
;     const unsigned char* sa = smem + cur * G8_STAGE_B;
;     const unsigned char* sb = sa + G8_TILE_B;
; #pragma unroll
;     for (int ks = 0; ks < 2; ++ks) {
;       bf16x8 At[8], Bf[4];
;       Bf[0] = *(const bf16x8*)(sb + lds_byte2(wc * 64 + fr, ks * 32 + fq * 8));
;       At[0] = *(const bf16x8*)(sa + lds_byte2(wr * 128 + fr, ks * 32 + fq * 8));
; #pragma unroll
;       for (int n = 1; n < 4; ++n) Bf[n] = *(const bf16x8*)(sb + lds_byte2(wc * 64 + n * 16 + fr, ks * 32 + fq * 8));
; #pragma unroll
;       for (int m = 1; m < 8; ++m) At[m] = *(const bf16x8*)(sa + lds_byte2(wr * 128 + m * 16 + fr, ks * 32 + fq * 8));
;       {
;         __builtin_amdgcn_sched_barrier(0);
;         if (t + 1 < nt) { G8_STAGE_R(cur ^ 1, Ab + (t + 1) * 64, Bb + (t + 1) * 64, 2 * ks, 2 * ks + 2); }
;         else if (has_next) { G8_STAGE_R(0, Abn, Bbn, 2 * ks, 2 * ks + 2); }
;         __builtin_amdgcn_sched_barrier(0);
;       }
; #pragma unroll
;       for (int m = 0; m < 8; ++m)
; #pragma unroll
;         for (int n = 0; n < 4; ++n) acc[m][n] = MFMA16(At[m], Bf[n], acc[m][n]);
;       __builtin_amdgcn_sched_barrier(0);
;     }
;     asm volatile("s_waitcnt vmcnt(0)" ::: "memory");
;     __syncthreads();
;   }
	ds_read_b128 v[158:161], v0 offset:32768
	ds_read_b128 v[162:165], v0 offset:34816
	v_mfma_f32_16x16x32_bf16 v[118:121], v[174:177], v[166:169], v[118:121]
	v_mfma_f32_16x16x32_bf16 v[114:117], v[174:177], v[170:173], v[114:117]
	ds_read_b128 v[174:177], v157
	v_mfma_f32_16x16x32_bf16 v[102:105], v[186:189], v[166:169], v[102:105]
	v_mfma_f32_16x16x32_bf16 v[98:101], v[186:189], v[170:173], v[98:101]
	ds_read_b128 v[186:189], v207
	v_mfma_f32_16x16x32_bf16 v[86:89], v[190:193], v[166:169], v[86:89]
	v_mfma_f32_16x16x32_bf16 v[82:85], v[190:193], v[170:173], v[82:85]
	ds_read_b128 v[190:193], v238
	v_mfma_f32_16x16x32_bf16 v[70:73], v[212:215], v[166:169], v[70:73]
	v_mfma_f32_16x16x32_bf16 v[66:69], v[212:215], v[170:173], v[66:69]
	ds_read_b128 v[212:215], v239
	v_mfma_f32_16x16x32_bf16 v[54:57], v[222:225], v[166:169], v[54:57]
	v_mfma_f32_16x16x32_bf16 v[50:53], v[222:225], v[170:173], v[50:53]
	ds_read_b128 v[222:225], v240
	v_mfma_f32_16x16x32_bf16 v[38:41], v[226:229], v[166:169], v[38:41]
	v_mfma_f32_16x16x32_bf16 v[34:37], v[226:229], v[170:173], v[34:37]
	ds_read_b128 v[226:229], v241
	v_mfma_f32_16x16x32_bf16 v[22:25], v[230:233], v[166:169], v[22:25]
	v_mfma_f32_16x16x32_bf16 v[18:21], v[230:233], v[170:173], v[18:21]
	ds_read_b128 v[230:233], v242
	v_mfma_f32_16x16x32_bf16 v[6:9], v[234:237], v[166:169], v[6:9]
	v_mfma_f32_16x16x32_bf16 v[2:5], v[234:237], v[170:173], v[2:5]
	ds_read_b128 v[234:237], v243
	ds_read_b128 v[166:169], v0 offset:36864
	ds_read_b128 v[170:173], v0 offset:38912
	s_add_u32 s0, s0, 0x80
	s_addc_u32 s1, s1, 0
	s_add_i32 s56, s56, 0x10000
	s_cmpk_eq_i32 s0, 0x1580
	s_cbranch_scc0 .LBB0_483
	s_waitcnt lgkmcnt(0)
	s_add_i32 s0, 0, 0x18000
	v_add_u32_e32 v0, s0, v155
	v_add_u32_e32 v0, v0, v153
	v_add_u32_e32 v130, s30, v155
	v_add_u32_e32 v190, v130, v156
	ds_read_b128 v[130:133], v0
	ds_read_b128 v[134:137], v0 offset:2048
	ds_read_b128 v[138:141], v0 offset:4096
	ds_read_b128 v[142:145], v0 offset:6144
	v_add_u32_e32 v154, s30, v154
	v_add_u32_e32 v192, v154, v152
	v_add_u32_e32 v207, v154, v149
	v_add_u32_e32 v209, v154, v147
	v_add_u32_e32 v191, v154, v150
	ds_read_b128 v[174:177], v190
	ds_read_b128 v[166:169], v191
	v_add_u32_e32 v193, v154, v151
	ds_read_b128 v[170:173], v192
	ds_read_b128 v[158:161], v193
	v_add_u32_e32 v208, v154, v148
	ds_read_b128 v[162:165], v207
	ds_read_b128 v[150:153], v208
	v_add_u32_e32 v212, v154, v146
	ds_read_b128 v[154:157], v209
	ds_read_b128 v[146:149], v212
	v_cndmask_b32_e64 v186, 0, 1, s[14:15]
	v_cmp_ne_u32_e64 s[0:1], 1, v186
	s_andn2_b64 vcc, exec, s[14:15]
	s_cbranch_vccnz .LBB0_486
	v_readfirstlane_b32 s14, v185
	v_lshl_add_u64 v[188:189], s[10:11], 0, v[178:179]
	v_lshl_add_u64 v[178:179], s[8:9], 0, v[178:179]
	s_mov_b32 m0, s14
	v_readfirstlane_b32 s14, v184
	global_load_lds_dwordx4 v[178:179], off
	s_mov_b32 m0, s14
	v_readfirstlane_b32 s14, v183
	v_lshl_add_u64 v[186:187], s[10:11], 0, v[180:181]
	v_lshl_add_u64 v[180:181], s[8:9], 0, v[180:181]
	global_load_lds_dwordx4 v[188:189], off
	s_mov_b32 m0, s14
	v_readfirstlane_b32 s14, v182
	global_load_lds_dwordx4 v[180:181], off
	s_mov_b32 m0, s14
	s_nop 0
	global_load_lds_dwordx4 v[186:187], off

; #define MFMA16(a, b, c) __builtin_amdgcn_mfma_f32_16x16x32_bf16((a), (b), (c), 0, 0, 0)
; template <class Epi>
; DI void gemm8_tile(const bf16_t* __restrict__ Ab, int lda, const bf16_t* __restrict__ Bb, int ldb, int K, int brow, int bcol, const Epi epi,
;                    bool staged, bool has_next, const bf16_t* __restrict__ Abn, const bf16_t* __restrict__ Bbn) {
;     ...
;   for (int t = 0; t < nt; ++t) {
;     const int cur = t & 1;
;     const unsigned char* sa = smem + cur * G8_STAGE_B;
;     const unsigned char* sb = sa + G8_TILE_B;
; #pragma unroll
;     for (int ks = 0; ks < 2; ++ks) {
;       bf16x8 At[8], Bf[4];
;       Bf[0] = *(const bf16x8*)(sb + lds_byte2(wc * 64 + fr, ks * 32 + fq * 8));
;       At[0] = *(const bf16x8*)(sa + lds_byte2(wr * 128 + fr, ks * 32 + fq * 8));
; #pragma unroll
;       for (int n = 1; n < 4; ++n) Bf[n] = *(const bf16x8*)(sb + lds_byte2(wc * 64 + n * 16 + fr, ks * 32 + fq * 8));
; #pragma unroll
;       for (int m = 1; m < 8; ++m) At[m] = *(const bf16x8*)(sa + lds_byte2(wr * 128 + m * 16 + fr, ks * 32 + fq * 8));
;       {
;         __builtin_amdgcn_sched_barrier(0);
;         if (t + 1 < nt) { G8_STAGE_R(cur ^ 1, Ab + (t + 1) * 64, Bb + (t + 1) * 64, 2 * ks, 2 * ks + 2); }
;         else if (has_next) { G8_STAGE_R(0, Abn, Bbn, 2 * ks, 2 * ks + 2); }
;         __builtin_amdgcn_sched_barrier(0);
;       }
; #pragma unroll
;       for (int m = 0; m < 8; ++m)
; #pragma unroll
;         for (int n = 0; n < 4; ++n) acc[m][n] = MFMA16(At[m], Bf[n], acc[m][n]);
;       __builtin_amdgcn_sched_barrier(0);
;     }
;     asm volatile("s_waitcnt vmcnt(0)" ::: "memory");
;     __syncthreads();
.LBB0_650:
	s_and_b32 s15, s14, 0x10000
	s_xor_b32 s31, s15, 0x10000
	v_add_u32_e32 v243, s31, v185
	s_nop 0
	v_readfirstlane_b32 s15, v243
	s_waitcnt lgkmcnt(8)
	v_mfma_f32_16x16x32_bf16 v[126:129], v[174:177], v[158:161], v[126:129]
	v_mfma_f32_16x16x32_bf16 v[122:125], v[174:177], v[162:165], v[122:125]
	s_mov_b32 m0, s15
	v_lshl_add_u64 v[234:235], v[144:145], 0, s[0:1]
	global_load_lds_dwordx4 v[234:235], off
	v_mfma_f32_16x16x32_bf16 v[110:113], v[186:189], v[158:161], v[110:113]
	v_mfma_f32_16x16x32_bf16 v[106:109], v[186:189], v[162:165], v[106:109]
	s_add_u32 m0, s15, 0x8000
	v_lshl_add_u64 v[234:235], v[136:137], 0, s[0:1]
	global_load_lds_dwordx4 v[234:235], off
	s_waitcnt lgkmcnt(6)
	v_mfma_f32_16x16x32_bf16 v[94:97], v[202:205], v[158:161], v[94:97]
	v_mfma_f32_16x16x32_bf16 v[90:93], v[202:205], v[162:165], v[90:93]
	s_add_u32 m0, s15, 0x2000
	v_lshl_add_u64 v[234:235], v[142:143], 0, s[0:1]
	global_load_lds_dwordx4 v[234:235], off
	v_mfma_f32_16x16x32_bf16 v[78:81], v[206:209], v[158:161], v[78:81]
	v_mfma_f32_16x16x32_bf16 v[74:77], v[206:209], v[162:165], v[74:77]
	s_add_u32 m0, s15, 0xa000
	v_lshl_add_u64 v[234:235], v[134:135], 0, s[0:1]
	global_load_lds_dwordx4 v[234:235], off
	s_waitcnt lgkmcnt(4)
	v_mfma_f32_16x16x32_bf16 v[62:65], v[212:215], v[158:161], v[62:65]
	v_mfma_f32_16x16x32_bf16 v[58:61], v[212:215], v[162:165], v[58:61]
	s_add_u32 m0, s15, 0x4000
	v_lshl_add_u64 v[234:235], v[140:141], 0, s[0:1]
	global_load_lds_dwordx4 v[234:235], off
	v_mfma_f32_16x16x32_bf16 v[46:49], v[222:225], v[158:161], v[46:49]
	v_mfma_f32_16x16x32_bf16 v[42:45], v[222:225], v[162:165], v[42:45]
	s_add_u32 m0, s15, 0xc000
	v_lshl_add_u64 v[234:235], v[132:133], 0, s[0:1]
	global_load_lds_dwordx4 v[234:235], off
	s_waitcnt lgkmcnt(2)
	v_mfma_f32_16x16x32_bf16 v[30:33], v[226:229], v[158:161], v[30:33]
	v_mfma_f32_16x16x32_bf16 v[26:29], v[226:229], v[162:165], v[26:29]
	s_add_u32 m0, s15, 0x6000
	v_lshl_add_u64 v[234:235], v[138:139], 0, s[0:1]
	global_load_lds_dwordx4 v[234:235], off
	v_mfma_f32_16x16x32_bf16 v[14:17], v[230:233], v[158:161], v[14:17]
	v_mfma_f32_16x16x32_bf16 v[10:13], v[230:233], v[162:165], v[10:13]
	s_add_u32 m0, s15, 0xe000
	v_lshl_add_u64 v[234:235], v[130:131], 0, s[0:1]
	global_load_lds_dwordx4 v[234:235], off
	ds_read_b128 v[158:161], v0 offset:33792
	ds_read_b128 v[162:165], v0 offset:35840
	s_waitcnt lgkmcnt(2)
	v_mfma_f32_16x16x32_bf16 v[118:121], v[174:177], v[166:169], v[118:121]
	v_mfma_f32_16x16x32_bf16 v[114:117], v[174:177], v[170:173], v[114:117]
	ds_read_b128 v[174:177], v157 offset:1024
	v_mfma_f32_16x16x32_bf16 v[102:105], v[186:189], v[166:169], v[102:105]
	v_mfma_f32_16x16x32_bf16 v[98:101], v[186:189], v[170:173], v[98:101]
	ds_read_b128 v[186:189], v236 offset:1024
	v_mfma_f32_16x16x32_bf16 v[86:89], v[202:205], v[166:169], v[86:89]
	v_mfma_f32_16x16x32_bf16 v[82:85], v[202:205], v[170:173], v[82:85]
	ds_read_b128 v[202:205], v237 offset:1024
	v_mfma_f32_16x16x32_bf16 v[70:73], v[206:209], v[166:169], v[70:73]
	v_mfma_f32_16x16x32_bf16 v[66:69], v[206:209], v[170:173], v[66:69]
	ds_read_b128 v[206:209], v238 offset:1024
	v_mfma_f32_16x16x32_bf16 v[54:57], v[212:215], v[166:169], v[54:57]
	v_mfma_f32_16x16x32_bf16 v[50:53], v[212:215], v[170:173], v[50:53]
	ds_read_b128 v[212:215], v239 offset:1024
	v_mfma_f32_16x16x32_bf16 v[38:41], v[222:225], v[166:169], v[38:41]
	v_mfma_f32_16x16x32_bf16 v[34:37], v[222:225], v[170:173], v[34:37]
	ds_read_b128 v[222:225], v240 offset:1024
	v_mfma_f32_16x16x32_bf16 v[22:25], v[226:229], v[166:169], v[22:25]
	v_mfma_f32_16x16x32_bf16 v[18:21], v[226:229], v[170:173], v[18:21]
	ds_read_b128 v[226:229], v241 offset:1024
	v_mfma_f32_16x16x32_bf16 v[6:9], v[230:233], v[166:169], v[6:9]
	v_mfma_f32_16x16x32_bf16 v[2:5], v[230:233], v[170:173], v[2:5]
	ds_read_b128 v[230:233], v242 offset:1024
	ds_read_b128 v[166:169], v0 offset:37888
	ds_read_b128 v[170:173], v0 offset:39936
	s_waitcnt lgkmcnt(8)
	v_mfma_f32_16x16x32_bf16 v[126:129], v[174:177], v[158:161], v[126:129]
	v_mfma_f32_16x16x32_bf16 v[122:125], v[174:177], v[162:165], v[122:125]
	v_add3_u32 v0, s31, v155, v153
	v_mfma_f32_16x16x32_bf16 v[110:113], v[186:189], v[158:161], v[110:113]
	v_mfma_f32_16x16x32_bf16 v[106:109], v[186:189], v[162:165], v[106:109]
	v_add3_u32 v157, s31, v155, v156
	s_waitcnt lgkmcnt(6)
	v_mfma_f32_16x16x32_bf16 v[94:97], v[202:205], v[158:161], v[94:97]
	v_mfma_f32_16x16x32_bf16 v[90:93], v[202:205], v[162:165], v[90:93]
	v_add3_u32 v237, s31, v154, v152
	v_mfma_f32_16x16x32_bf16 v[78:81], v[206:209], v[158:161], v[78:81]
	v_mfma_f32_16x16x32_bf16 v[74:77], v[206:209], v[162:165], v[74:77]
	v_add3_u32 v239, s31, v154, v149
	s_waitcnt lgkmcnt(4)
	v_mfma_f32_16x16x32_bf16 v[62:65], v[212:215], v[158:161], v[62:65]
	v_mfma_f32_16x16x32_bf16 v[58:61], v[212:215], v[162:165], v[58:61]
	v_add3_u32 v241, s31, v154, v147
	v_mfma_f32_16x16x32_bf16 v[46:49], v[222:225], v[158:161], v[46:49]
	v_mfma_f32_16x16x32_bf16 v[42:45], v[222:225], v[162:165], v[42:45]
	v_add3_u32 v236, s31, v154, v150
	s_waitcnt lgkmcnt(2)
	v_mfma_f32_16x16x32_bf16 v[30:33], v[226:229], v[158:161], v[30:33]
	v_mfma_f32_16x16x32_bf16 v[26:29], v[226:229], v[162:165], v[26:29]
	v_add3_u32 v238, s31, v154, v151
	v_mfma_f32_16x16x32_bf16 v[14:17], v[230:233], v[158:161], v[14:17]
	v_mfma_f32_16x16x32_bf16 v[10:13], v[230:233], v[162:165], v[10:13]
	v_add3_u32 v240, s31, v154, v148
	v_add3_u32 v242, s31, v154, v146
	s_waitcnt vmcnt(0) lgkmcnt(0)
	s_barrier
; #define MFMA16(a, b, c) __builtin_amdgcn_mfma_f32_16x16x32_bf16((a), (b), (c), 0, 0, 0)
; template <class Epi>
; DI void gemm8_tile(const bf16_t* __restrict__ Ab, int lda, const bf16_t* __restrict__ Bb, int ldb, int K, int brow, int bcol, const Epi epi,
;                    bool staged, bool has_next, const bf16_t* __restrict__ Abn, const bf16_t* __restrict__ Bbn) {
;     ...
;   for (int t = 0; t < nt; ++t) {
;     const int cur = t & 1;
;     const unsigned char* sa = smem + cur * G8_STAGE_B;
;     const unsigned char* sb = sa + G8_TILE_B;
; #pragma unroll
;     for (int ks = 0; ks < 2; ++ks) {
;       bf16x8 At[8], Bf[4];
;       Bf[0] = *(const bf16x8*)(sb + lds_byte2(wc * 64 + fr, ks * 32 + fq * 8));
;       At[0] = *(const bf16x8*)(sa + lds_byte2(wr * 128 + fr, ks * 32 + fq * 8));
; #pragma unroll
;       for (int n = 1; n < 4; ++n) Bf[n] = *(const bf16x8*)(sb + lds_byte2(wc * 64 + n * 16 + fr, ks * 32 + fq * 8));
; #pragma unroll
;       for (int m = 1; m < 8; ++m) At[m] = *(const bf16x8*)(sa + lds_byte2(wr * 128 + m * 16 + fr, ks * 32 + fq * 8));
;       {
;         __builtin_amdgcn_sched_barrier(0);
;         if (t + 1 < nt) { G8_STAGE_R(cur ^ 1, Ab + (t + 1) * 64, Bb + (t + 1) * 64, 2 * ks, 2 * ks + 2); }
;         else if (has_next) { G8_STAGE_R(0, Abn, Bbn, 2 * ks, 2 * ks + 2); }
;         __builtin_amdgcn_sched_barrier(0);
;       }
; #pragma unroll
;       for (int m = 0; m < 8; ++m)
; #pragma unroll
;         for (int n = 0; n < 4; ++n) acc[m][n] = MFMA16(At[m], Bf[n], acc[m][n]);
;       __builtin_amdgcn_sched_barrier(0);
;     }
;     asm volatile("s_waitcnt vmcnt(0)" ::: "memory");
;     __syncthreads();
;   }
	ds_read_b128 v[158:161], v0 offset:32768
	ds_read_b128 v[162:165], v0 offset:34816
	v_mfma_f32_16x16x32_bf16 v[118:121], v[174:177], v[166:169], v[118:121]
	v_mfma_f32_16x16x32_bf16 v[114:117], v[174:177], v[170:173], v[114:117]
	ds_read_b128 v[174:177], v157
	v_mfma_f32_16x16x32_bf16 v[102:105], v[186:189], v[166:169], v[102:105]
	v_mfma_f32_16x16x32_bf16 v[98:101], v[186:189], v[170:173], v[98:101]
	ds_read_b128 v[186:189], v236
	v_mfma_f32_16x16x32_bf16 v[86:89], v[202:205], v[166:169], v[86:89]
	v_mfma_f32_16x16x32_bf16 v[82:85], v[202:205], v[170:173], v[82:85]
	ds_read_b128 v[202:205], v237
	v_mfma_f32_16x16x32_bf16 v[70:73], v[206:209], v[166:169], v[70:73]
	v_mfma_f32_16x16x32_bf16 v[66:69], v[206:209], v[170:173], v[66:69]
	ds_read_b128 v[206:209], v238
	v_mfma_f32_16x16x32_bf16 v[54:57], v[212:215], v[166:169], v[54:57]
	v_mfma_f32_16x16x32_bf16 v[50:53], v[212:215], v[170:173], v[50:53]
	ds_read_b128 v[212:215], v239
	v_mfma_f32_16x16x32_bf16 v[38:41], v[222:225], v[166:169], v[38:41]
	v_mfma_f32_16x16x32_bf16 v[34:37], v[222:225], v[170:173], v[34:37]
	ds_read_b128 v[222:225], v240
	v_mfma_f32_16x16x32_bf16 v[22:25], v[226:229], v[166:169], v[22:25]
	v_mfma_f32_16x16x32_bf16 v[18:21], v[226:229], v[170:173], v[18:21]
	ds_read_b128 v[226:229], v241
	v_mfma_f32_16x16x32_bf16 v[6:9], v[230:233], v[166:169], v[6:9]
	v_mfma_f32_16x16x32_bf16 v[2:5], v[230:233], v[170:173], v[2:5]
	ds_read_b128 v[230:233], v242
	ds_read_b128 v[166:169], v0 offset:36864
	ds_read_b128 v[170:173], v0 offset:38912
	s_add_u32 s0, s0, 0x80
	s_addc_u32 s1, s1, 0
	s_add_i32 s14, s14, 0x10000
	s_cmpk_eq_i32 s0, 0x780
	s_cbranch_scc0 .LBB0_650
	s_waitcnt lgkmcnt(0)
	s_add_i32 s0, 0, 0x18000
	v_add_u32_e32 v0, s0, v155
	v_add_u32_e32 v0, v0, v153
	v_add_u32_e32 v130, s30, v155
	v_add_u32_e32 v186, v130, v156
	ds_read_b128 v[130:133], v0
	ds_read_b128 v[134:137], v0 offset:2048
	ds_read_b128 v[138:141], v0 offset:4096
	ds_read_b128 v[142:145], v0 offset:6144
	v_add_u32_e32 v154, s30, v154
	v_add_u32_e32 v203, v154, v152
	v_add_u32_e32 v205, v154, v149
	v_add_u32_e32 v207, v154, v147
	v_add_u32_e32 v202, v154, v150
	ds_read_b128 v[174:177], v186
	ds_read_b128 v[166:169], v202
	v_add_u32_e32 v204, v154, v151
	ds_read_b128 v[170:173], v203
	ds_read_b128 v[158:161], v204
	v_add_u32_e32 v206, v154, v148
	ds_read_b128 v[162:165], v205
	ds_read_b128 v[150:153], v206
	v_add_u32_e32 v208, v154, v146
	ds_read_b128 v[154:157], v207
	ds_read_b128 v[146:149], v208
	v_cndmask_b32_e64 v187, 0, 1, s[12:13]
	v_cmp_ne_u32_e64 s[0:1], 1, v187
	s_andn2_b64 vcc, exec, s[12:13]
	s_cbranch_vccnz .LBB0_653
	v_readfirstlane_b32 s12, v185
	v_lshl_add_u64 v[188:189], s[8:9], 0, v[180:181]
	s_mov_b32 m0, s12
	v_readfirstlane_b32 s12, v184
	v_lshl_add_u64 v[180:181], s[10:11], 0, v[180:181]
	global_load_lds_dwordx4 v[188:189], off
	s_mov_b32 m0, s12
	v_readfirstlane_b32 s12, v183
	v_lshl_add_u64 v[212:213], s[8:9], 0, v[178:179]
	global_load_lds_dwordx4 v[180:181], off
	s_mov_b32 m0, s12
	v_readfirstlane_b32 s12, v182
	v_lshl_add_u64 v[178:179], s[10:11], 0, v[178:179]
	global_load_lds_dwordx4 v[212:213], off
	s_mov_b32 m0, s12
	s_nop 0
	global_load_lds_dwordx4 v[178:179], off

; #define MFMA16(a, b, c) __builtin_amdgcn_mfma_f32_16x16x32_bf16((a), (b), (c), 0, 0, 0)
; template <class Epi>
; DI void gemm8_tile(const bf16_t* __restrict__ Ab, int lda, const bf16_t* __restrict__ Bb, int ldb, int K, int brow, int bcol, const Epi epi,
;                    bool staged, bool has_next, const bf16_t* __restrict__ Abn, const bf16_t* __restrict__ Bbn) {
;     ...
;   for (int t = 0; t < nt; ++t) {
;     const int cur = t & 1;
;     const unsigned char* sa = smem + cur * G8_STAGE_B;
;     const unsigned char* sb = sa + G8_TILE_B;
; #pragma unroll
;     for (int ks = 0; ks < 2; ++ks) {
;       bf16x8 At[8], Bf[4];
;       Bf[0] = *(const bf16x8*)(sb + lds_byte2(wc * 64 + fr, ks * 32 + fq * 8));
;       At[0] = *(const bf16x8*)(sa + lds_byte2(wr * 128 + fr, ks * 32 + fq * 8));
; #pragma unroll
;       for (int n = 1; n < 4; ++n) Bf[n] = *(const bf16x8*)(sb + lds_byte2(wc * 64 + n * 16 + fr, ks * 32 + fq * 8));
; #pragma unroll
;       for (int m = 1; m < 8; ++m) At[m] = *(const bf16x8*)(sa + lds_byte2(wr * 128 + m * 16 + fr, ks * 32 + fq * 8));
;       {
;         __builtin_amdgcn_sched_barrier(0);
;         if (t + 1 < nt) { G8_STAGE_R(cur ^ 1, Ab + (t + 1) * 64, Bb + (t + 1) * 64, 2 * ks, 2 * ks + 2); }
;         else if (has_next) { G8_STAGE_R(0, Abn, Bbn, 2 * ks, 2 * ks + 2); }
;         __builtin_amdgcn_sched_barrier(0);
;       }
; #pragma unroll
;       for (int m = 0; m < 8; ++m)
; #pragma unroll
;         for (int n = 0; n < 4; ++n) acc[m][n] = MFMA16(At[m], Bf[n], acc[m][n]);
;       __builtin_amdgcn_sched_barrier(0);
;     }
;     asm volatile("s_waitcnt vmcnt(0)" ::: "memory");
;     __syncthreads();
.LBB0_1254:
	s_and_b32 s39, s38, 0x10000
	s_xor_b32 s54, s39, 0x10000
	v_add_u32_e32 v250, s54, v203
	s_nop 0
	v_readfirstlane_b32 s39, v250
	s_waitcnt lgkmcnt(8)
	v_mfma_f32_16x16x32_bf16 v[126:129], v[174:177], v[158:161], v[126:129]
	v_mfma_f32_16x16x32_bf16 v[122:125], v[174:177], v[162:165], v[122:125]
	s_mov_b32 m0, s39
	v_lshl_add_u64 v[208:209], v[144:145], 0, s[0:1]
	global_load_lds_dwordx4 v[208:209], off
	v_mfma_f32_16x16x32_bf16 v[110:113], v[204:207], v[158:161], v[110:113]
	v_mfma_f32_16x16x32_bf16 v[106:109], v[204:207], v[162:165], v[106:109]
	s_add_u32 m0, s39, 0x8000
	v_lshl_add_u64 v[208:209], v[136:137], 0, s[0:1]
	global_load_lds_dwordx4 v[208:209], off
	s_waitcnt lgkmcnt(6)
	v_mfma_f32_16x16x32_bf16 v[94:97], v[212:215], v[158:161], v[94:97]
	v_mfma_f32_16x16x32_bf16 v[90:93], v[212:215], v[162:165], v[90:93]
	s_add_u32 m0, s39, 0x2000
	v_lshl_add_u64 v[208:209], v[142:143], 0, s[0:1]
	global_load_lds_dwordx4 v[208:209], off
	v_mfma_f32_16x16x32_bf16 v[78:81], v[222:225], v[158:161], v[78:81]
	v_mfma_f32_16x16x32_bf16 v[74:77], v[222:225], v[162:165], v[74:77]
	s_add_u32 m0, s39, 0xa000
	v_lshl_add_u64 v[208:209], v[134:135], 0, s[0:1]
	global_load_lds_dwordx4 v[208:209], off
	s_waitcnt lgkmcnt(4)
	v_mfma_f32_16x16x32_bf16 v[62:65], v[226:229], v[158:161], v[62:65]
	v_mfma_f32_16x16x32_bf16 v[58:61], v[226:229], v[162:165], v[58:61]
	s_add_u32 m0, s39, 0x4000
	v_lshl_add_u64 v[208:209], v[140:141], 0, s[0:1]
	global_load_lds_dwordx4 v[208:209], off
	v_mfma_f32_16x16x32_bf16 v[46:49], v[230:233], v[158:161], v[46:49]
	v_mfma_f32_16x16x32_bf16 v[42:45], v[230:233], v[162:165], v[42:45]
	s_add_u32 m0, s39, 0xc000
	v_lshl_add_u64 v[208:209], v[132:133], 0, s[0:1]
	global_load_lds_dwordx4 v[208:209], off
	s_waitcnt lgkmcnt(2)
	v_mfma_f32_16x16x32_bf16 v[30:33], v[234:237], v[158:161], v[30:33]
	v_mfma_f32_16x16x32_bf16 v[26:29], v[234:237], v[162:165], v[26:29]
	s_add_u32 m0, s39, 0x6000
	v_lshl_add_u64 v[208:209], v[138:139], 0, s[0:1]
	global_load_lds_dwordx4 v[208:209], off
	v_mfma_f32_16x16x32_bf16 v[14:17], v[238:241], v[158:161], v[14:17]
	v_mfma_f32_16x16x32_bf16 v[10:13], v[238:241], v[162:165], v[10:13]
	s_add_u32 m0, s39, 0xe000
	v_lshl_add_u64 v[208:209], v[130:131], 0, s[0:1]
	global_load_lds_dwordx4 v[208:209], off
	ds_read_b128 v[158:161], v157 offset:33792
	ds_read_b128 v[162:165], v157 offset:35840
	s_waitcnt lgkmcnt(2)
	v_mfma_f32_16x16x32_bf16 v[118:121], v[174:177], v[166:169], v[118:121]
	v_mfma_f32_16x16x32_bf16 v[114:117], v[174:177], v[170:173], v[114:117]
	ds_read_b128 v[174:177], v242 offset:1024
	v_mfma_f32_16x16x32_bf16 v[102:105], v[204:207], v[166:169], v[102:105]
	v_mfma_f32_16x16x32_bf16 v[98:101], v[204:207], v[170:173], v[98:101]
	ds_read_b128 v[204:207], v243 offset:1024
	v_mfma_f32_16x16x32_bf16 v[86:89], v[212:215], v[166:169], v[86:89]
	v_mfma_f32_16x16x32_bf16 v[82:85], v[212:215], v[170:173], v[82:85]
	ds_read_b128 v[212:215], v244 offset:1024
	v_mfma_f32_16x16x32_bf16 v[70:73], v[222:225], v[166:169], v[70:73]
	v_mfma_f32_16x16x32_bf16 v[66:69], v[222:225], v[170:173], v[66:69]
	ds_read_b128 v[222:225], v245 offset:1024
	v_mfma_f32_16x16x32_bf16 v[54:57], v[226:229], v[166:169], v[54:57]
	v_mfma_f32_16x16x32_bf16 v[50:53], v[226:229], v[170:173], v[50:53]
	ds_read_b128 v[226:229], v246 offset:1024
	v_mfma_f32_16x16x32_bf16 v[38:41], v[230:233], v[166:169], v[38:41]
	v_mfma_f32_16x16x32_bf16 v[34:37], v[230:233], v[170:173], v[34:37]
	ds_read_b128 v[230:233], v247 offset:1024
	v_mfma_f32_16x16x32_bf16 v[22:25], v[234:237], v[166:169], v[22:25]
	v_mfma_f32_16x16x32_bf16 v[18:21], v[234:237], v[170:173], v[18:21]
	ds_read_b128 v[234:237], v248 offset:1024
	v_mfma_f32_16x16x32_bf16 v[6:9], v[238:241], v[166:169], v[6:9]
	v_mfma_f32_16x16x32_bf16 v[2:5], v[238:241], v[170:173], v[2:5]
	ds_read_b128 v[238:241], v249 offset:1024
	ds_read_b128 v[166:169], v157 offset:37888
	ds_read_b128 v[170:173], v157 offset:39936
	s_waitcnt lgkmcnt(8)
	v_mfma_f32_16x16x32_bf16 v[126:129], v[174:177], v[158:161], v[126:129]
	v_mfma_f32_16x16x32_bf16 v[122:125], v[174:177], v[162:165], v[122:125]
	v_add3_u32 v157, s54, v155, v153
	v_mfma_f32_16x16x32_bf16 v[110:113], v[204:207], v[158:161], v[110:113]
	v_mfma_f32_16x16x32_bf16 v[106:109], v[204:207], v[162:165], v[106:109]
	v_add3_u32 v242, s54, v155, v156
	s_waitcnt lgkmcnt(6)
	v_mfma_f32_16x16x32_bf16 v[94:97], v[212:215], v[158:161], v[94:97]
	v_mfma_f32_16x16x32_bf16 v[90:93], v[212:215], v[162:165], v[90:93]
	v_add3_u32 v244, s54, v154, v152
	v_mfma_f32_16x16x32_bf16 v[78:81], v[222:225], v[158:161], v[78:81]
	v_mfma_f32_16x16x32_bf16 v[74:77], v[222:225], v[162:165], v[74:77]
	v_add3_u32 v246, s54, v154, v149
	s_waitcnt lgkmcnt(4)
	v_mfma_f32_16x16x32_bf16 v[62:65], v[226:229], v[158:161], v[62:65]
	v_mfma_f32_16x16x32_bf16 v[58:61], v[226:229], v[162:165], v[58:61]
	v_add3_u32 v248, s54, v154, v147
	v_mfma_f32_16x16x32_bf16 v[46:49], v[230:233], v[158:161], v[46:49]
	v_mfma_f32_16x16x32_bf16 v[42:45], v[230:233], v[162:165], v[42:45]
	v_add3_u32 v243, s54, v154, v150
	s_waitcnt lgkmcnt(2)
	v_mfma_f32_16x16x32_bf16 v[30:33], v[234:237], v[158:161], v[30:33]
	v_mfma_f32_16x16x32_bf16 v[26:29], v[234:237], v[162:165], v[26:29]
	v_add3_u32 v245, s54, v154, v151
	v_mfma_f32_16x16x32_bf16 v[14:17], v[238:241], v[158:161], v[14:17]
	v_mfma_f32_16x16x32_bf16 v[10:13], v[238:241], v[162:165], v[10:13]
	v_add3_u32 v247, s54, v154, v148
	v_add3_u32 v249, s54, v154, v146
	s_waitcnt vmcnt(0) lgkmcnt(0)
	s_barrier
; #define MFMA16(a, b, c) __builtin_amdgcn_mfma_f32_16x16x32_bf16((a), (b), (c), 0, 0, 0)
; template <class Epi>
; DI void gemm8_tile(const bf16_t* __restrict__ Ab, int lda, const bf16_t* __restrict__ Bb, int ldb, int K, int brow, int bcol, const Epi epi,
;                    bool staged, bool has_next, const bf16_t* __restrict__ Abn, const bf16_t* __restrict__ Bbn) {
;     ...
;   for (int t = 0; t < nt; ++t) {
;     const int cur = t & 1;
;     const unsigned char* sa = smem + cur * G8_STAGE_B;
;     const unsigned char* sb = sa + G8_TILE_B;
; #pragma unroll
;     for (int ks = 0; ks < 2; ++ks) {
;       bf16x8 At[8], Bf[4];
;       Bf[0] = *(const bf16x8*)(sb + lds_byte2(wc * 64 + fr, ks * 32 + fq * 8));
;       At[0] = *(const bf16x8*)(sa + lds_byte2(wr * 128 + fr, ks * 32 + fq * 8));
; #pragma unroll
;       for (int n = 1; n < 4; ++n) Bf[n] = *(const bf16x8*)(sb + lds_byte2(wc * 64 + n * 16 + fr, ks * 32 + fq * 8));
; #pragma unroll
;       for (int m = 1; m < 8; ++m) At[m] = *(const bf16x8*)(sa + lds_byte2(wr * 128 + m * 16 + fr, ks * 32 + fq * 8));
;       {
;         __builtin_amdgcn_sched_barrier(0);
;         if (t + 1 < nt) { G8_STAGE_R(cur ^ 1, Ab + (t + 1) * 64, Bb + (t + 1) * 64, 2 * ks, 2 * ks + 2); }
;         else if (has_next) { G8_STAGE_R(0, Abn, Bbn, 2 * ks, 2 * ks + 2); }
;         __builtin_amdgcn_sched_barrier(0);
;       }
; #pragma unroll
;       for (int m = 0; m < 8; ++m)
; #pragma unroll
;         for (int n = 0; n < 4; ++n) acc[m][n] = MFMA16(At[m], Bf[n], acc[m][n]);
;       __builtin_amdgcn_sched_barrier(0);
;     }
;     asm volatile("s_waitcnt vmcnt(0)" ::: "memory");
;     __syncthreads();
;   }
	ds_read_b128 v[158:161], v157 offset:32768
	ds_read_b128 v[162:165], v157 offset:34816
	v_mfma_f32_16x16x32_bf16 v[118:121], v[174:177], v[166:169], v[118:121]
	v_mfma_f32_16x16x32_bf16 v[114:117], v[174:177], v[170:173], v[114:117]
	ds_read_b128 v[174:177], v242
	v_mfma_f32_16x16x32_bf16 v[102:105], v[204:207], v[166:169], v[102:105]
	v_mfma_f32_16x16x32_bf16 v[98:101], v[204:207], v[170:173], v[98:101]
	ds_read_b128 v[204:207], v243
	v_mfma_f32_16x16x32_bf16 v[86:89], v[212:215], v[166:169], v[86:89]
	v_mfma_f32_16x16x32_bf16 v[82:85], v[212:215], v[170:173], v[82:85]
	ds_read_b128 v[212:215], v244
	v_mfma_f32_16x16x32_bf16 v[70:73], v[222:225], v[166:169], v[70:73]
	v_mfma_f32_16x16x32_bf16 v[66:69], v[222:225], v[170:173], v[66:69]
	ds_read_b128 v[222:225], v245
	v_mfma_f32_16x16x32_bf16 v[54:57], v[226:229], v[166:169], v[54:57]
	v_mfma_f32_16x16x32_bf16 v[50:53], v[226:229], v[170:173], v[50:53]
	ds_read_b128 v[226:229], v246
	v_mfma_f32_16x16x32_bf16 v[38:41], v[230:233], v[166:169], v[38:41]
	v_mfma_f32_16x16x32_bf16 v[34:37], v[230:233], v[170:173], v[34:37]
	ds_read_b128 v[230:233], v247
	v_mfma_f32_16x16x32_bf16 v[22:25], v[234:237], v[166:169], v[22:25]
	v_mfma_f32_16x16x32_bf16 v[18:21], v[234:237], v[170:173], v[18:21]
	ds_read_b128 v[234:237], v248
	v_mfma_f32_16x16x32_bf16 v[6:9], v[238:241], v[166:169], v[6:9]
	v_mfma_f32_16x16x32_bf16 v[2:5], v[238:241], v[170:173], v[2:5]
	ds_read_b128 v[238:241], v249
	ds_read_b128 v[166:169], v157 offset:36864
	ds_read_b128 v[170:173], v157 offset:38912
	s_add_u32 s0, s0, 0x80
	s_addc_u32 s1, s1, 0
	s_add_i32 s38, s38, 0x10000
	s_cmpk_eq_i32 s0, 0x580
	s_cbranch_scc0 .LBB0_1254
	s_waitcnt lgkmcnt(0)
	s_add_i32 s0, 0, 0x18000
	v_add_u32_e32 v130, s0, v155
	v_add_u32_e32 v204, v130, v153
	v_add_u32_e32 v130, s30, v155
	v_add_u32_e32 v205, v130, v156
	ds_read_b128 v[130:133], v204
	ds_read_b128 v[134:137], v204 offset:2048
	ds_read_b128 v[138:141], v204 offset:4096
	ds_read_b128 v[142:145], v204 offset:6144
	v_add_u32_e32 v154, s30, v154
	v_add_u32_e32 v207, v154, v152
	v_add_u32_e32 v209, v154, v149
	v_add_u32_e32 v213, v154, v147
	v_add_u32_e32 v206, v154, v150
	ds_read_b128 v[174:177], v205
	ds_read_b128 v[166:169], v206
	v_add_u32_e32 v208, v154, v151
	ds_read_b128 v[170:173], v207
	ds_read_b128 v[158:161], v208
	v_add_u32_e32 v212, v154, v148
	ds_read_b128 v[162:165], v209
	ds_read_b128 v[150:153], v212
	v_add_u32_e32 v214, v154, v146
	ds_read_b128 v[154:157], v213
	ds_read_b128 v[146:149], v214
	v_cndmask_b32_e64 v215, 0, 1, s[14:15]
	v_cmp_ne_u32_e64 s[0:1], 1, v215
	s_andn2_b64 vcc, exec, s[14:15]
	s_cbranch_vccnz .LBB0_1257
	v_readfirstlane_b32 s14, v203
	v_lshl_add_u64 v[184:185], v[184:185], 1, s[10:11]
	s_mov_b32 m0, s14
	v_readfirstlane_b32 s14, v202
	v_lshl_add_u64 v[186:187], v[186:187], 1, s[12:13]
	global_load_lds_dwordx4 v[184:185], off
	s_mov_b32 m0, s14
	v_readfirstlane_b32 s14, v201
	v_lshl_add_u64 v[188:189], v[188:189], 1, s[10:11]
	global_load_lds_dwordx4 v[186:187], off
	s_mov_b32 m0, s14
	v_readfirstlane_b32 s14, v200
	v_lshl_add_u64 v[190:191], v[190:191], 1, s[12:13]
	global_load_lds_dwordx4 v[188:189], off
	s_mov_b32 m0, s14
	s_nop 0
	global_load_lds_dwordx4 v[190:191], off

; #define MFMA16(a, b, c) __builtin_amdgcn_mfma_f32_16x16x32_bf16((a), (b), (c), 0, 0, 0)
; template <class Epi>
; DI void gemm8_tile(const bf16_t* __restrict__ Ab, int lda, const bf16_t* __restrict__ Bb, int ldb, int K, int brow, int bcol, const Epi epi,
;                    bool staged, bool has_next, const bf16_t* __restrict__ Abn, const bf16_t* __restrict__ Bbn) {
;     ...
;   for (int t = 0; t < nt; ++t) {
;     const int cur = t & 1;
;     const unsigned char* sa = smem + cur * G8_STAGE_B;
;     const unsigned char* sb = sa + G8_TILE_B;
; #pragma unroll
;     for (int ks = 0; ks < 2; ++ks) {
;       bf16x8 At[8], Bf[4];
;       Bf[0] = *(const bf16x8*)(sb + lds_byte2(wc * 64 + fr, ks * 32 + fq * 8));
;       At[0] = *(const bf16x8*)(sa + lds_byte2(wr * 128 + fr, ks * 32 + fq * 8));
; #pragma unroll
;       for (int n = 1; n < 4; ++n) Bf[n] = *(const bf16x8*)(sb + lds_byte2(wc * 64 + n * 16 + fr, ks * 32 + fq * 8));
; #pragma unroll
;       for (int m = 1; m < 8; ++m) At[m] = *(const bf16x8*)(sa + lds_byte2(wr * 128 + m * 16 + fr, ks * 32 + fq * 8));
;       {
;         __builtin_amdgcn_sched_barrier(0);
;         if (t + 1 < nt) { G8_STAGE_R(cur ^ 1, Ab + (t + 1) * 64, Bb + (t + 1) * 64, 2 * ks, 2 * ks + 2); }
;         else if (has_next) { G8_STAGE_R(0, Abn, Bbn, 2 * ks, 2 * ks + 2); }
;         __builtin_amdgcn_sched_barrier(0);
;       }
; #pragma unroll
;       for (int m = 0; m < 8; ++m)
; #pragma unroll
;         for (int n = 0; n < 4; ++n) acc[m][n] = MFMA16(At[m], Bf[n], acc[m][n]);
;       __builtin_amdgcn_sched_barrier(0);
;     }
;     asm volatile("s_waitcnt vmcnt(0)" ::: "memory");
;     __syncthreads();
.LBB0_1312:
	s_and_b32 s39, s38, 0x10000
	s_xor_b32 s54, s39, 0x10000
	v_add_u32_e32 v244, s54, v185
	s_nop 0
	v_readfirstlane_b32 s39, v244
	s_waitcnt lgkmcnt(8)
	v_mfma_f32_16x16x32_bf16 v[126:129], v[174:177], v[158:161], v[126:129]
	v_mfma_f32_16x16x32_bf16 v[122:125], v[174:177], v[162:165], v[122:125]
	s_mov_b32 m0, s39
	v_lshl_add_u64 v[208:209], v[130:131], 0, s[0:1]
	global_load_lds_dwordx4 v[208:209], off
	v_mfma_f32_16x16x32_bf16 v[110:113], v[186:189], v[158:161], v[110:113]
	v_mfma_f32_16x16x32_bf16 v[106:109], v[186:189], v[162:165], v[106:109]
	s_add_u32 m0, s39, 0x8000
	v_lshl_add_u64 v[208:209], v[138:139], 0, s[0:1]
	global_load_lds_dwordx4 v[208:209], off
	s_waitcnt lgkmcnt(6)
	v_mfma_f32_16x16x32_bf16 v[94:97], v[190:193], v[158:161], v[94:97]
	v_mfma_f32_16x16x32_bf16 v[90:93], v[190:193], v[162:165], v[90:93]
	s_add_u32 m0, s39, 0x2000
	v_lshl_add_u64 v[208:209], v[132:133], 0, s[0:1]
	global_load_lds_dwordx4 v[208:209], off
	v_mfma_f32_16x16x32_bf16 v[78:81], v[212:215], v[158:161], v[78:81]
	v_mfma_f32_16x16x32_bf16 v[74:77], v[212:215], v[162:165], v[74:77]
	s_add_u32 m0, s39, 0xa000
	v_lshl_add_u64 v[208:209], v[140:141], 0, s[0:1]
	global_load_lds_dwordx4 v[208:209], off
	s_waitcnt lgkmcnt(4)
	v_mfma_f32_16x16x32_bf16 v[62:65], v[222:225], v[158:161], v[62:65]
	v_mfma_f32_16x16x32_bf16 v[58:61], v[222:225], v[162:165], v[58:61]
	s_add_u32 m0, s39, 0x4000
	v_lshl_add_u64 v[208:209], v[134:135], 0, s[0:1]
	global_load_lds_dwordx4 v[208:209], off
	v_mfma_f32_16x16x32_bf16 v[46:49], v[226:229], v[158:161], v[46:49]
	v_mfma_f32_16x16x32_bf16 v[42:45], v[226:229], v[162:165], v[42:45]
	s_add_u32 m0, s39, 0xc000
	v_lshl_add_u64 v[208:209], v[142:143], 0, s[0:1]
	global_load_lds_dwordx4 v[208:209], off
	s_waitcnt lgkmcnt(2)
	v_mfma_f32_16x16x32_bf16 v[30:33], v[230:233], v[158:161], v[30:33]
	v_mfma_f32_16x16x32_bf16 v[26:29], v[230:233], v[162:165], v[26:29]
	s_add_u32 m0, s39, 0x6000
	v_lshl_add_u64 v[208:209], v[136:137], 0, s[0:1]
	global_load_lds_dwordx4 v[208:209], off
	v_mfma_f32_16x16x32_bf16 v[14:17], v[234:237], v[158:161], v[14:17]
	v_mfma_f32_16x16x32_bf16 v[10:13], v[234:237], v[162:165], v[10:13]
	s_add_u32 m0, s39, 0xe000
	v_lshl_add_u64 v[208:209], v[144:145], 0, s[0:1]
	global_load_lds_dwordx4 v[208:209], off
	ds_read_b128 v[158:161], v0 offset:33792
	ds_read_b128 v[162:165], v0 offset:35840
	s_waitcnt lgkmcnt(2)
	v_mfma_f32_16x16x32_bf16 v[118:121], v[174:177], v[166:169], v[118:121]
	v_mfma_f32_16x16x32_bf16 v[114:117], v[174:177], v[170:173], v[114:117]
	ds_read_b128 v[174:177], v157 offset:1024
	v_mfma_f32_16x16x32_bf16 v[102:105], v[186:189], v[166:169], v[102:105]
	v_mfma_f32_16x16x32_bf16 v[98:101], v[186:189], v[170:173], v[98:101]
	ds_read_b128 v[186:189], v207 offset:1024
	v_mfma_f32_16x16x32_bf16 v[86:89], v[190:193], v[166:169], v[86:89]
	v_mfma_f32_16x16x32_bf16 v[82:85], v[190:193], v[170:173], v[82:85]
	ds_read_b128 v[190:193], v238 offset:1024
	v_mfma_f32_16x16x32_bf16 v[70:73], v[212:215], v[166:169], v[70:73]
	v_mfma_f32_16x16x32_bf16 v[66:69], v[212:215], v[170:173], v[66:69]
	ds_read_b128 v[212:215], v239 offset:1024
	v_mfma_f32_16x16x32_bf16 v[54:57], v[222:225], v[166:169], v[54:57]
	v_mfma_f32_16x16x32_bf16 v[50:53], v[222:225], v[170:173], v[50:53]
	ds_read_b128 v[222:225], v240 offset:1024
	v_mfma_f32_16x16x32_bf16 v[38:41], v[226:229], v[166:169], v[38:41]
	v_mfma_f32_16x16x32_bf16 v[34:37], v[226:229], v[170:173], v[34:37]
	ds_read_b128 v[226:229], v241 offset:1024
	v_mfma_f32_16x16x32_bf16 v[22:25], v[230:233], v[166:169], v[22:25]
	v_mfma_f32_16x16x32_bf16 v[18:21], v[230:233], v[170:173], v[18:21]
	ds_read_b128 v[230:233], v242 offset:1024
	v_mfma_f32_16x16x32_bf16 v[6:9], v[234:237], v[166:169], v[6:9]
	v_mfma_f32_16x16x32_bf16 v[2:5], v[234:237], v[170:173], v[2:5]
	ds_read_b128 v[234:237], v243 offset:1024
	ds_read_b128 v[166:169], v0 offset:37888
	ds_read_b128 v[170:173], v0 offset:39936
	s_waitcnt lgkmcnt(8)
	v_mfma_f32_16x16x32_bf16 v[126:129], v[174:177], v[158:161], v[126:129]
	v_mfma_f32_16x16x32_bf16 v[122:125], v[174:177], v[162:165], v[122:125]
	v_add3_u32 v0, s54, v155, v153
	v_mfma_f32_16x16x32_bf16 v[110:113], v[186:189], v[158:161], v[110:113]
	v_mfma_f32_16x16x32_bf16 v[106:109], v[186:189], v[162:165], v[106:109]
	v_add3_u32 v157, s54, v155, v156
	s_waitcnt lgkmcnt(6)
	v_mfma_f32_16x16x32_bf16 v[94:97], v[190:193], v[158:161], v[94:97]
	v_mfma_f32_16x16x32_bf16 v[90:93], v[190:193], v[162:165], v[90:93]
	v_add3_u32 v238, s54, v154, v152
	v_mfma_f32_16x16x32_bf16 v[78:81], v[212:215], v[158:161], v[78:81]
	v_mfma_f32_16x16x32_bf16 v[74:77], v[212:215], v[162:165], v[74:77]
	v_add3_u32 v240, s54, v154, v149
	s_waitcnt lgkmcnt(4)
	v_mfma_f32_16x16x32_bf16 v[62:65], v[222:225], v[158:161], v[62:65]
	v_mfma_f32_16x16x32_bf16 v[58:61], v[222:225], v[162:165], v[58:61]
	v_add3_u32 v242, s54, v154, v147
	v_mfma_f32_16x16x32_bf16 v[46:49], v[226:229], v[158:161], v[46:49]
	v_mfma_f32_16x16x32_bf16 v[42:45], v[226:229], v[162:165], v[42:45]
	v_add3_u32 v207, s54, v154, v150
	s_waitcnt lgkmcnt(2)
	v_mfma_f32_16x16x32_bf16 v[30:33], v[230:233], v[158:161], v[30:33]
	v_mfma_f32_16x16x32_bf16 v[26:29], v[230:233], v[162:165], v[26:29]
	v_add3_u32 v239, s54, v154, v151
	v_mfma_f32_16x16x32_bf16 v[14:17], v[234:237], v[158:161], v[14:17]
	v_mfma_f32_16x16x32_bf16 v[10:13], v[234:237], v[162:165], v[10:13]
	v_add3_u32 v241, s54, v154, v148
	v_add3_u32 v243, s54, v154, v146
	s_waitcnt vmcnt(0) lgkmcnt(0)
	s_barrier
; #define MFMA16(a, b, c) __builtin_amdgcn_mfma_f32_16x16x32_bf16((a), (b), (c), 0, 0, 0)
; template <class Epi>
; DI void gemm8_tile(const bf16_t* __restrict__ Ab, int lda, const bf16_t* __restrict__ Bb, int ldb, int K, int brow, int bcol, const Epi epi,
;                    bool staged, bool has_next, const bf16_t* __restrict__ Abn, const bf16_t* __restrict__ Bbn) {
;     ...
;   for (int t = 0; t < nt; ++t) {
;     const int cur = t & 1;
;     const unsigned char* sa = smem + cur * G8_STAGE_B;
;     const unsigned char* sb = sa + G8_TILE_B;
; #pragma unroll
;     for (int ks = 0; ks < 2; ++ks) {
;       bf16x8 At[8], Bf[4];
;       Bf[0] = *(const bf16x8*)(sb + lds_byte2(wc * 64 + fr, ks * 32 + fq * 8));
;       At[0] = *(const bf16x8*)(sa + lds_byte2(wr * 128 + fr, ks * 32 + fq * 8));
; #pragma unroll
;       for (int n = 1; n < 4; ++n) Bf[n] = *(const bf16x8*)(sb + lds_byte2(wc * 64 + n * 16 + fr, ks * 32 + fq * 8));
; #pragma unroll
;       for (int m = 1; m < 8; ++m) At[m] = *(const bf16x8*)(sa + lds_byte2(wr * 128 + m * 16 + fr, ks * 32 + fq * 8));
;       {
;         __builtin_amdgcn_sched_barrier(0);
;         if (t + 1 < nt) { G8_STAGE_R(cur ^ 1, Ab + (t + 1) * 64, Bb + (t + 1) * 64, 2 * ks, 2 * ks + 2); }
;         else if (has_next) { G8_STAGE_R(0, Abn, Bbn, 2 * ks, 2 * ks + 2); }
;         __builtin_amdgcn_sched_barrier(0);
;       }
; #pragma unroll
;       for (int m = 0; m < 8; ++m)
; #pragma unroll
;         for (int n = 0; n < 4; ++n) acc[m][n] = MFMA16(At[m], Bf[n], acc[m][n]);
;       __builtin_amdgcn_sched_barrier(0);
;     }
;     asm volatile("s_waitcnt vmcnt(0)" ::: "memory");
;     __syncthreads();
;   }
	ds_read_b128 v[158:161], v0 offset:32768
	ds_read_b128 v[162:165], v0 offset:34816
	v_mfma_f32_16x16x32_bf16 v[118:121], v[174:177], v[166:169], v[118:121]
	v_mfma_f32_16x16x32_bf16 v[114:117], v[174:177], v[170:173], v[114:117]
	ds_read_b128 v[174:177], v157
	v_mfma_f32_16x16x32_bf16 v[102:105], v[186:189], v[166:169], v[102:105]
	v_mfma_f32_16x16x32_bf16 v[98:101], v[186:189], v[170:173], v[98:101]
	ds_read_b128 v[186:189], v207
	v_mfma_f32_16x16x32_bf16 v[86:89], v[190:193], v[166:169], v[86:89]
	v_mfma_f32_16x16x32_bf16 v[82:85], v[190:193], v[170:173], v[82:85]
	ds_read_b128 v[190:193], v238
	v_mfma_f32_16x16x32_bf16 v[70:73], v[212:215], v[166:169], v[70:73]
	v_mfma_f32_16x16x32_bf16 v[66:69], v[212:215], v[170:173], v[66:69]
	ds_read_b128 v[212:215], v239
	v_mfma_f32_16x16x32_bf16 v[54:57], v[222:225], v[166:169], v[54:57]
	v_mfma_f32_16x16x32_bf16 v[50:53], v[222:225], v[170:173], v[50:53]
	ds_read_b128 v[222:225], v240
	v_mfma_f32_16x16x32_bf16 v[38:41], v[226:229], v[166:169], v[38:41]
	v_mfma_f32_16x16x32_bf16 v[34:37], v[226:229], v[170:173], v[34:37]
	ds_read_b128 v[226:229], v241
	v_mfma_f32_16x16x32_bf16 v[22:25], v[230:233], v[166:169], v[22:25]
	v_mfma_f32_16x16x32_bf16 v[18:21], v[230:233], v[170:173], v[18:21]
	ds_read_b128 v[230:233], v242
	v_mfma_f32_16x16x32_bf16 v[6:9], v[234:237], v[166:169], v[6:9]
	v_mfma_f32_16x16x32_bf16 v[2:5], v[234:237], v[170:173], v[2:5]
	ds_read_b128 v[234:237], v243
	ds_read_b128 v[166:169], v0 offset:36864
	ds_read_b128 v[170:173], v0 offset:38912
	s_add_u32 s0, s0, 0x80
	s_addc_u32 s1, s1, 0
	s_add_i32 s38, s38, 0x10000
	s_cmpk_eq_i32 s0, 0x780
	s_cbranch_scc0 .LBB0_1312
	s_waitcnt lgkmcnt(0)
	s_add_i32 s0, 0, 0x18000
	v_add_u32_e32 v0, s0, v155
	v_add_u32_e32 v0, v0, v153
	v_add_u32_e32 v130, s30, v155
	v_add_u32_e32 v190, v130, v156
	ds_read_b128 v[130:133], v0
	ds_read_b128 v[134:137], v0 offset:2048
	ds_read_b128 v[138:141], v0 offset:4096
	ds_read_b128 v[142:145], v0 offset:6144
	v_add_u32_e32 v154, s30, v154
	v_add_u32_e32 v192, v154, v152
	v_add_u32_e32 v207, v154, v149
	v_add_u32_e32 v209, v154, v147
	v_add_u32_e32 v191, v154, v150
	ds_read_b128 v[174:177], v190
	ds_read_b128 v[166:169], v191
	v_add_u32_e32 v193, v154, v151
	ds_read_b128 v[170:173], v192
	ds_read_b128 v[158:161], v193
	v_add_u32_e32 v208, v154, v148
	ds_read_b128 v[162:165], v207
	ds_read_b128 v[150:153], v208
	v_add_u32_e32 v212, v154, v146
	ds_read_b128 v[154:157], v209
	ds_read_b128 v[146:149], v212
	v_cndmask_b32_e64 v186, 0, 1, s[14:15]
	v_cmp_ne_u32_e64 s[0:1], 1, v186
	s_andn2_b64 vcc, exec, s[14:15]
	s_cbranch_vccnz .LBB0_1315
	v_readfirstlane_b32 s14, v185
	v_lshl_add_u64 v[188:189], s[10:11], 0, v[178:179]
	v_lshl_add_u64 v[178:179], s[8:9], 0, v[178:179]
	s_mov_b32 m0, s14
	v_readfirstlane_b32 s14, v184
	global_load_lds_dwordx4 v[178:179], off
	s_mov_b32 m0, s14
	v_readfirstlane_b32 s14, v183
	v_lshl_add_u64 v[186:187], s[10:11], 0, v[180:181]
	v_lshl_add_u64 v[180:181], s[8:9], 0, v[180:181]
	global_load_lds_dwordx4 v[188:189], off
	s_mov_b32 m0, s14
	v_readfirstlane_b32 s14, v182
	global_load_lds_dwordx4 v[180:181], off
	s_mov_b32 m0, s14
	s_nop 0
	global_load_lds_dwordx4 v[186:187], off

; #define MFMA16(a, b, c) __builtin_amdgcn_mfma_f32_16x16x32_bf16((a), (b), (c), 0, 0, 0)
; template <class Epi>
; DI void gemm8_tile(const bf16_t* __restrict__ Ab, int lda, const bf16_t* __restrict__ Bb, int ldb, int K, int brow, int bcol, const Epi epi,
;                    bool staged, bool has_next, const bf16_t* __restrict__ Abn, const bf16_t* __restrict__ Bbn) {
;     ...
;   for (int t = 0; t < nt; ++t) {
;     const int cur = t & 1;
;     const unsigned char* sa = smem + cur * G8_STAGE_B;
;     const unsigned char* sb = sa + G8_TILE_B;
; #pragma unroll
;     for (int ks = 0; ks < 2; ++ks) {
;       bf16x8 At[8], Bf[4];
;       Bf[0] = *(const bf16x8*)(sb + lds_byte2(wc * 64 + fr, ks * 32 + fq * 8));
;       At[0] = *(const bf16x8*)(sa + lds_byte2(wr * 128 + fr, ks * 32 + fq * 8));
; #pragma unroll
;       for (int n = 1; n < 4; ++n) Bf[n] = *(const bf16x8*)(sb + lds_byte2(wc * 64 + n * 16 + fr, ks * 32 + fq * 8));
; #pragma unroll
;       for (int m = 1; m < 8; ++m) At[m] = *(const bf16x8*)(sa + lds_byte2(wr * 128 + m * 16 + fr, ks * 32 + fq * 8));
;       {
;         __builtin_amdgcn_sched_barrier(0);
;         if (t + 1 < nt) { G8_STAGE_R(cur ^ 1, Ab + (t + 1) * 64, Bb + (t + 1) * 64, 2 * ks, 2 * ks + 2); }
;         else if (has_next) { G8_STAGE_R(0, Abn, Bbn, 2 * ks, 2 * ks + 2); }
;         __builtin_amdgcn_sched_barrier(0);
;       }
; #pragma unroll
;       for (int m = 0; m < 8; ++m)
; #pragma unroll
;         for (int n = 0; n < 4; ++n) acc[m][n] = MFMA16(At[m], Bf[n], acc[m][n]);
;       __builtin_amdgcn_sched_barrier(0);
;     }
;     asm volatile("s_waitcnt vmcnt(0)" ::: "memory");
;     __syncthreads();
.LBB0_1510:
	s_and_b32 s14, s9, 0x10000
	s_xor_b32 s15, s14, 0x10000
	v_add_u32_e32 v251, s15, v189
	s_nop 0
	v_readfirstlane_b32 s14, v251
	s_waitcnt lgkmcnt(8)
	v_mfma_f32_16x16x32_bf16 v[126:129], v[174:177], v[158:161], v[126:129]
	v_mfma_f32_16x16x32_bf16 v[122:125], v[174:177], v[162:165], v[122:125]
	s_mov_b32 m0, s14
	v_lshl_add_u64 v[242:243], v[130:131], 0, s[0:1]
	global_load_lds_dwordx4 v[242:243], off
	v_mfma_f32_16x16x32_bf16 v[110:113], v[190:193], v[158:161], v[110:113]
	v_mfma_f32_16x16x32_bf16 v[106:109], v[190:193], v[162:165], v[106:109]
	s_add_u32 m0, s14, 0x8000
	v_lshl_add_u64 v[242:243], v[138:139], 0, s[0:1]
	global_load_lds_dwordx4 v[242:243], off
	s_waitcnt lgkmcnt(6)
	v_mfma_f32_16x16x32_bf16 v[94:97], v[212:215], v[158:161], v[94:97]
	v_mfma_f32_16x16x32_bf16 v[90:93], v[212:215], v[162:165], v[90:93]
	s_add_u32 m0, s14, 0x2000
	v_lshl_add_u64 v[242:243], v[132:133], 0, s[0:1]
	global_load_lds_dwordx4 v[242:243], off
	v_mfma_f32_16x16x32_bf16 v[78:81], v[222:225], v[158:161], v[78:81]
	v_mfma_f32_16x16x32_bf16 v[74:77], v[222:225], v[162:165], v[74:77]
	s_add_u32 m0, s14, 0xa000
	v_lshl_add_u64 v[242:243], v[140:141], 0, s[0:1]
	global_load_lds_dwordx4 v[242:243], off
	s_waitcnt lgkmcnt(4)
	v_mfma_f32_16x16x32_bf16 v[62:65], v[226:229], v[158:161], v[62:65]
	v_mfma_f32_16x16x32_bf16 v[58:61], v[226:229], v[162:165], v[58:61]
	s_add_u32 m0, s14, 0x4000
	v_lshl_add_u64 v[242:243], v[134:135], 0, s[0:1]
	global_load_lds_dwordx4 v[242:243], off
	v_mfma_f32_16x16x32_bf16 v[46:49], v[230:233], v[158:161], v[46:49]
	v_mfma_f32_16x16x32_bf16 v[42:45], v[230:233], v[162:165], v[42:45]
	s_add_u32 m0, s14, 0xc000
	v_lshl_add_u64 v[242:243], v[142:143], 0, s[0:1]
	global_load_lds_dwordx4 v[242:243], off
	s_waitcnt lgkmcnt(2)
	v_mfma_f32_16x16x32_bf16 v[30:33], v[234:237], v[158:161], v[30:33]
	v_mfma_f32_16x16x32_bf16 v[26:29], v[234:237], v[162:165], v[26:29]
	s_add_u32 m0, s14, 0x6000
	v_lshl_add_u64 v[242:243], v[136:137], 0, s[0:1]
	global_load_lds_dwordx4 v[242:243], off
	v_mfma_f32_16x16x32_bf16 v[14:17], v[238:241], v[158:161], v[14:17]
	v_mfma_f32_16x16x32_bf16 v[10:13], v[238:241], v[162:165], v[10:13]
	s_add_u32 m0, s14, 0xe000
	v_lshl_add_u64 v[242:243], v[144:145], 0, s[0:1]
	global_load_lds_dwordx4 v[242:243], off
	ds_read_b128 v[158:161], v157 offset:33792
	ds_read_b128 v[162:165], v157 offset:35840
	s_waitcnt lgkmcnt(2)
	v_mfma_f32_16x16x32_bf16 v[118:121], v[174:177], v[166:169], v[118:121]
	v_mfma_f32_16x16x32_bf16 v[114:117], v[174:177], v[170:173], v[114:117]
	ds_read_b128 v[174:177], v209 offset:1024
	v_mfma_f32_16x16x32_bf16 v[102:105], v[190:193], v[166:169], v[102:105]
	v_mfma_f32_16x16x32_bf16 v[98:101], v[190:193], v[170:173], v[98:101]
	ds_read_b128 v[190:193], v244 offset:1024
	v_mfma_f32_16x16x32_bf16 v[86:89], v[212:215], v[166:169], v[86:89]
	v_mfma_f32_16x16x32_bf16 v[82:85], v[212:215], v[170:173], v[82:85]
	ds_read_b128 v[212:215], v245 offset:1024
	v_mfma_f32_16x16x32_bf16 v[70:73], v[222:225], v[166:169], v[70:73]
	v_mfma_f32_16x16x32_bf16 v[66:69], v[222:225], v[170:173], v[66:69]
	ds_read_b128 v[222:225], v246 offset:1024
	v_mfma_f32_16x16x32_bf16 v[54:57], v[226:229], v[166:169], v[54:57]
	v_mfma_f32_16x16x32_bf16 v[50:53], v[226:229], v[170:173], v[50:53]
	ds_read_b128 v[226:229], v247 offset:1024
	v_mfma_f32_16x16x32_bf16 v[38:41], v[230:233], v[166:169], v[38:41]
	v_mfma_f32_16x16x32_bf16 v[34:37], v[230:233], v[170:173], v[34:37]
	ds_read_b128 v[230:233], v248 offset:1024
	v_mfma_f32_16x16x32_bf16 v[22:25], v[234:237], v[166:169], v[22:25]
	v_mfma_f32_16x16x32_bf16 v[18:21], v[234:237], v[170:173], v[18:21]
	ds_read_b128 v[234:237], v249 offset:1024
	v_mfma_f32_16x16x32_bf16 v[6:9], v[238:241], v[166:169], v[6:9]
	v_mfma_f32_16x16x32_bf16 v[2:5], v[238:241], v[170:173], v[2:5]
	ds_read_b128 v[238:241], v250 offset:1024
	ds_read_b128 v[166:169], v157 offset:37888
	ds_read_b128 v[170:173], v157 offset:39936
	s_waitcnt lgkmcnt(8)
	v_mfma_f32_16x16x32_bf16 v[126:129], v[174:177], v[158:161], v[126:129]
	v_mfma_f32_16x16x32_bf16 v[122:125], v[174:177], v[162:165], v[122:125]
	v_add3_u32 v157, s15, v155, v153
	v_mfma_f32_16x16x32_bf16 v[110:113], v[190:193], v[158:161], v[110:113]
	v_mfma_f32_16x16x32_bf16 v[106:109], v[190:193], v[162:165], v[106:109]
	v_add3_u32 v209, s15, v155, v156
	s_waitcnt lgkmcnt(6)
	v_mfma_f32_16x16x32_bf16 v[94:97], v[212:215], v[158:161], v[94:97]
	v_mfma_f32_16x16x32_bf16 v[90:93], v[212:215], v[162:165], v[90:93]
	v_add3_u32 v245, s15, v154, v152
	v_mfma_f32_16x16x32_bf16 v[78:81], v[222:225], v[158:161], v[78:81]
	v_mfma_f32_16x16x32_bf16 v[74:77], v[222:225], v[162:165], v[74:77]
	v_add3_u32 v247, s15, v154, v149
	s_waitcnt lgkmcnt(4)
	v_mfma_f32_16x16x32_bf16 v[62:65], v[226:229], v[158:161], v[62:65]
	v_mfma_f32_16x16x32_bf16 v[58:61], v[226:229], v[162:165], v[58:61]
	v_add3_u32 v249, s15, v154, v147
	v_mfma_f32_16x16x32_bf16 v[46:49], v[230:233], v[158:161], v[46:49]
	v_mfma_f32_16x16x32_bf16 v[42:45], v[230:233], v[162:165], v[42:45]
	v_add3_u32 v244, s15, v154, v150
	s_waitcnt lgkmcnt(2)
	v_mfma_f32_16x16x32_bf16 v[30:33], v[234:237], v[158:161], v[30:33]
	v_mfma_f32_16x16x32_bf16 v[26:29], v[234:237], v[162:165], v[26:29]
	v_add3_u32 v246, s15, v154, v151
	v_mfma_f32_16x16x32_bf16 v[14:17], v[238:241], v[158:161], v[14:17]
	v_mfma_f32_16x16x32_bf16 v[10:13], v[238:241], v[162:165], v[10:13]
	v_add3_u32 v248, s15, v154, v148
	v_add3_u32 v250, s15, v154, v146
	s_waitcnt vmcnt(0) lgkmcnt(0)
	s_barrier
; template <class Epi>
; DI void gemm8_tile(const bf16_t* __restrict__ Ab, int lda, const bf16_t* __restrict__ Bb, int ldb, int K, int brow, int bcol, const Epi epi,
;                    bool staged, bool has_next, const bf16_t* __restrict__ Abn, const bf16_t* __restrict__ Bbn) {
;     ...
;   for (int t = 0; t < nt; ++t) {
;     const int cur = t & 1;
;     const unsigned char* sa = smem + cur * G8_STAGE_B;
;     const unsigned char* sb = sa + G8_TILE_B;
; #pragma unroll
;     for (int ks = 0; ks < 2; ++ks) {
;       bf16x8 At[8], Bf[4];
;       Bf[0] = *(const bf16x8*)(sb + lds_byte2(wc * 64 + fr, ks * 32 + fq * 8));
;       At[0] = *(const bf16x8*)(sa + lds_byte2(wr * 128 + fr, ks * 32 + fq * 8));
; #pragma unroll
;       for (int n = 1; n < 4; ++n) Bf[n] = *(const bf16x8*)(sb + lds_byte2(wc * 64 + n * 16 + fr, ks * 32 + fq * 8));
; #pragma unroll
;       for (int m = 1; m < 8; ++m) At[m] = *(const bf16x8*)(sa + lds_byte2(wr * 128 + m * 16 + fr, ks * 32 + fq * 8));
;       {
;         __builtin_amdgcn_sched_barrier(0);
;         if (t + 1 < nt) { G8_STAGE_R(cur ^ 1, Ab + (t + 1) * 64, Bb + (t + 1) * 64, 2 * ks, 2 * ks + 2); }
;         else if (has_next) { G8_STAGE_R(0, Abn, Bbn, 2 * ks, 2 * ks + 2); }
;         __builtin_amdgcn_sched_barrier(0);
;       }
	ds_read_b128 v[158:161], v157 offset:32768
	ds_read_b128 v[162:165], v157 offset:34816
	v_mfma_f32_16x16x32_bf16 v[118:121], v[174:177], v[166:169], v[118:121]
	v_mfma_f32_16x16x32_bf16 v[114:117], v[174:177], v[170:173], v[114:117]
	ds_read_b128 v[174:177], v209
	v_mfma_f32_16x16x32_bf16 v[102:105], v[190:193], v[166:169], v[102:105]
	v_mfma_f32_16x16x32_bf16 v[98:101], v[190:193], v[170:173], v[98:101]
	ds_read_b128 v[190:193], v244
	v_mfma_f32_16x16x32_bf16 v[86:89], v[212:215], v[166:169], v[86:89]
	v_mfma_f32_16x16x32_bf16 v[82:85], v[212:215], v[170:173], v[82:85]
	ds_read_b128 v[212:215], v245
	v_mfma_f32_16x16x32_bf16 v[70:73], v[222:225], v[166:169], v[70:73]
	v_mfma_f32_16x16x32_bf16 v[66:69], v[222:225], v[170:173], v[66:69]
	ds_read_b128 v[222:225], v246
	v_mfma_f32_16x16x32_bf16 v[54:57], v[226:229], v[166:169], v[54:57]
	v_mfma_f32_16x16x32_bf16 v[50:53], v[226:229], v[170:173], v[50:53]
	ds_read_b128 v[226:229], v247
	v_mfma_f32_16x16x32_bf16 v[38:41], v[230:233], v[166:169], v[38:41]
	v_mfma_f32_16x16x32_bf16 v[34:37], v[230:233], v[170:173], v[34:37]
	ds_read_b128 v[230:233], v248
	v_mfma_f32_16x16x32_bf16 v[22:25], v[234:237], v[166:169], v[22:25]
	v_mfma_f32_16x16x32_bf16 v[18:21], v[234:237], v[170:173], v[18:21]
	ds_read_b128 v[234:237], v249
	v_mfma_f32_16x16x32_bf16 v[6:9], v[238:241], v[166:169], v[6:9]
	v_mfma_f32_16x16x32_bf16 v[2:5], v[238:241], v[170:173], v[2:5]
	ds_read_b128 v[238:241], v250
	ds_read_b128 v[166:169], v157 offset:36864
	ds_read_b128 v[170:173], v157 offset:38912
	s_add_u32 s0, s0, 0x80
	s_addc_u32 s1, s1, 0
	s_add_i32 s9, s9, 0x10000
	s_cmpk_eq_i32 s0, 0x180
	s_cbranch_scc0 .LBB0_1510
	s_waitcnt lgkmcnt(0)
	s_add_i32 s0, 0, 0x18000
	v_add_u32_e32 v130, s0, v155
	v_add_u32_e32 v190, v130, v153
	v_add_u32_e32 v130, s30, v155
	v_add_u32_e32 v191, v130, v156
	ds_read_b128 v[130:133], v190
	ds_read_b128 v[134:137], v190 offset:2048
	ds_read_b128 v[138:141], v190 offset:4096
	ds_read_b128 v[142:145], v190 offset:6144
	v_add_u32_e32 v154, s30, v154
	v_add_u32_e32 v193, v154, v152
	v_add_u32_e32 v212, v154, v149
	v_add_u32_e32 v214, v154, v147
	v_add_u32_e32 v192, v154, v150
	ds_read_b128 v[174:177], v191
	ds_read_b128 v[166:169], v192
	v_add_u32_e32 v209, v154, v151
	ds_read_b128 v[170:173], v193
	ds_read_b128 v[158:161], v209
	v_add_u32_e32 v213, v154, v148
	ds_read_b128 v[162:165], v212
	ds_read_b128 v[150:153], v213
	v_add_u32_e32 v215, v154, v146
	ds_read_b128 v[154:157], v214
	ds_read_b128 v[146:149], v215
	v_cndmask_b32_e64 v222, 0, 1, s[38:39]
	v_cmp_ne_u32_e64 s[0:1], 1, v222
	s_andn2_b64 vcc, exec, s[38:39]
	s_movk_i32 s79, 0xffe0
	s_cbranch_vccnz .LBB0_1513
	v_readfirstlane_b32 s9, v189
	v_lshl_add_u64 v[178:179], v[178:179], 1, s[10:11]
	s_mov_b32 m0, s9
	v_readfirstlane_b32 s9, v188
	v_lshl_add_u64 v[180:181], v[180:181], 1, s[12:13]
	global_load_lds_dwordx4 v[178:179], off
	s_mov_b32 m0, s9
	v_readfirstlane_b32 s9, v187
	v_lshl_add_u64 v[182:183], v[182:183], 1, s[10:11]
	global_load_lds_dwordx4 v[180:181], off
	s_mov_b32 m0, s9
	v_readfirstlane_b32 s9, v186
	v_lshl_add_u64 v[184:185], v[184:185], 1, s[12:13]
	global_load_lds_dwordx4 v[182:183], off
	s_mov_b32 m0, s9
	s_nop 0
	global_load_lds_dwordx4 v[184:185], off

; #define MFMA16(a, b, c) __builtin_amdgcn_mfma_f32_16x16x32_bf16((a), (b), (c), 0, 0, 0)
; template <class Epi>
; DI void gemm8_tile(const bf16_t* __restrict__ Ab, int lda, const bf16_t* __restrict__ Bb, int ldb, int K, int brow, int bcol, const Epi epi,
;                    bool staged, bool has_next, const bf16_t* __restrict__ Abn, const bf16_t* __restrict__ Bbn) {
;     ...
;   for (int t = 0; t < nt; ++t) {
;     const int cur = t & 1;
;     const unsigned char* sa = smem + cur * G8_STAGE_B;
;     const unsigned char* sb = sa + G8_TILE_B;
; #pragma unroll
;     for (int ks = 0; ks < 2; ++ks) {
;       bf16x8 At[8], Bf[4];
;       Bf[0] = *(const bf16x8*)(sb + lds_byte2(wc * 64 + fr, ks * 32 + fq * 8));
;       At[0] = *(const bf16x8*)(sa + lds_byte2(wr * 128 + fr, ks * 32 + fq * 8));
; #pragma unroll
;       for (int n = 1; n < 4; ++n) Bf[n] = *(const bf16x8*)(sb + lds_byte2(wc * 64 + n * 16 + fr, ks * 32 + fq * 8));
; #pragma unroll
;       for (int m = 1; m < 8; ++m) At[m] = *(const bf16x8*)(sa + lds_byte2(wr * 128 + m * 16 + fr, ks * 32 + fq * 8));
;       {
;         __builtin_amdgcn_sched_barrier(0);
;         if (t + 1 < nt) { G8_STAGE_R(cur ^ 1, Ab + (t + 1) * 64, Bb + (t + 1) * 64, 2 * ks, 2 * ks + 2); }
;         else if (has_next) { G8_STAGE_R(0, Abn, Bbn, 2 * ks, 2 * ks + 2); }
;         __builtin_amdgcn_sched_barrier(0);
;       }
; #pragma unroll
;       for (int m = 0; m < 8; ++m)
; #pragma unroll
;         for (int n = 0; n < 4; ++n) acc[m][n] = MFMA16(At[m], Bf[n], acc[m][n]);
;       __builtin_amdgcn_sched_barrier(0);
;     }
;     asm volatile("s_waitcnt vmcnt(0)" ::: "memory");
;     __syncthreads();
.LBB0_1673:
	s_and_b32 s15, s14, 0x10000
	s_xor_b32 s38, s15, 0x10000
	v_add_u32_e32 v244, s38, v157
	s_nop 0
	v_readfirstlane_b32 s15, v244
	s_waitcnt lgkmcnt(8)
	v_mfma_f32_16x16x32_bf16 v[126:129], v[184:187], v[168:171], v[126:129]
	v_mfma_f32_16x16x32_bf16 v[122:125], v[184:187], v[172:175], v[122:125]
	s_mov_b32 m0, s15
	v_lshl_add_u64 v[160:161], v[144:145], 0, s[0:1]
	global_load_lds_dwordx4 v[160:161], off
	v_mfma_f32_16x16x32_bf16 v[110:113], v[188:191], v[168:171], v[110:113]
	v_mfma_f32_16x16x32_bf16 v[106:109], v[188:191], v[172:175], v[106:109]
	s_add_u32 m0, s15, 0x8000
	v_lshl_add_u64 v[160:161], v[136:137], 0, s[0:1]
	global_load_lds_dwordx4 v[160:161], off
	s_waitcnt lgkmcnt(6)
	v_mfma_f32_16x16x32_bf16 v[94:97], v[192:195], v[168:171], v[94:97]
	v_mfma_f32_16x16x32_bf16 v[90:93], v[192:195], v[172:175], v[90:93]
	s_add_u32 m0, s15, 0x2000
	v_lshl_add_u64 v[160:161], v[142:143], 0, s[0:1]
	global_load_lds_dwordx4 v[160:161], off
	v_mfma_f32_16x16x32_bf16 v[78:81], v[196:199], v[168:171], v[78:81]
	v_mfma_f32_16x16x32_bf16 v[74:77], v[196:199], v[172:175], v[74:77]
	s_add_u32 m0, s15, 0xa000
	v_lshl_add_u64 v[160:161], v[134:135], 0, s[0:1]
	global_load_lds_dwordx4 v[160:161], off
	s_waitcnt lgkmcnt(4)
	v_mfma_f32_16x16x32_bf16 v[62:65], v[200:203], v[168:171], v[62:65]
	v_mfma_f32_16x16x32_bf16 v[58:61], v[200:203], v[172:175], v[58:61]
	s_add_u32 m0, s15, 0x4000
	v_lshl_add_u64 v[160:161], v[140:141], 0, s[0:1]
	global_load_lds_dwordx4 v[160:161], off
	v_mfma_f32_16x16x32_bf16 v[46:49], v[204:207], v[168:171], v[46:49]
	v_mfma_f32_16x16x32_bf16 v[42:45], v[204:207], v[172:175], v[42:45]
	s_add_u32 m0, s15, 0xc000
	v_lshl_add_u64 v[160:161], v[132:133], 0, s[0:1]
	global_load_lds_dwordx4 v[160:161], off
	s_waitcnt lgkmcnt(2)
	v_mfma_f32_16x16x32_bf16 v[30:33], v[232:235], v[168:171], v[30:33]
	v_mfma_f32_16x16x32_bf16 v[26:29], v[232:235], v[172:175], v[26:29]
	s_add_u32 m0, s15, 0x6000
	v_lshl_add_u64 v[160:161], v[138:139], 0, s[0:1]
	global_load_lds_dwordx4 v[160:161], off
	v_mfma_f32_16x16x32_bf16 v[14:17], v[236:239], v[168:171], v[14:17]
	v_mfma_f32_16x16x32_bf16 v[10:13], v[236:239], v[172:175], v[10:13]
	s_add_u32 m0, s15, 0xe000
	v_lshl_add_u64 v[160:161], v[130:131], 0, s[0:1]
	global_load_lds_dwordx4 v[160:161], off
	ds_read_b128 v[168:171], v0 offset:33792
	ds_read_b128 v[172:175], v0 offset:35840
	s_waitcnt lgkmcnt(2)
	v_mfma_f32_16x16x32_bf16 v[118:121], v[184:187], v[176:179], v[118:121]
	v_mfma_f32_16x16x32_bf16 v[114:117], v[184:187], v[180:183], v[114:117]
	ds_read_b128 v[184:187], v159 offset:1024
	v_mfma_f32_16x16x32_bf16 v[102:105], v[188:191], v[176:179], v[102:105]
	v_mfma_f32_16x16x32_bf16 v[98:101], v[188:191], v[180:183], v[98:101]
	ds_read_b128 v[188:191], v208 offset:1024
	v_mfma_f32_16x16x32_bf16 v[86:89], v[192:195], v[176:179], v[86:89]
	v_mfma_f32_16x16x32_bf16 v[82:85], v[192:195], v[180:183], v[82:85]
	ds_read_b128 v[192:195], v209 offset:1024
	v_mfma_f32_16x16x32_bf16 v[70:73], v[196:199], v[176:179], v[70:73]
	v_mfma_f32_16x16x32_bf16 v[66:69], v[196:199], v[180:183], v[66:69]
	ds_read_b128 v[196:199], v231 offset:1024
	v_mfma_f32_16x16x32_bf16 v[54:57], v[200:203], v[176:179], v[54:57]
	v_mfma_f32_16x16x32_bf16 v[50:53], v[200:203], v[180:183], v[50:53]
	ds_read_b128 v[200:203], v240 offset:1024
	v_mfma_f32_16x16x32_bf16 v[38:41], v[204:207], v[176:179], v[38:41]
	v_mfma_f32_16x16x32_bf16 v[34:37], v[204:207], v[180:183], v[34:37]
	ds_read_b128 v[204:207], v241 offset:1024
	v_mfma_f32_16x16x32_bf16 v[22:25], v[232:235], v[176:179], v[22:25]
	v_mfma_f32_16x16x32_bf16 v[18:21], v[232:235], v[180:183], v[18:21]
	ds_read_b128 v[232:235], v242 offset:1024
	v_mfma_f32_16x16x32_bf16 v[6:9], v[236:239], v[176:179], v[6:9]
	v_mfma_f32_16x16x32_bf16 v[2:5], v[236:239], v[180:183], v[2:5]
	ds_read_b128 v[236:239], v243 offset:1024
	ds_read_b128 v[176:179], v0 offset:37888
	ds_read_b128 v[180:183], v0 offset:39936
	s_waitcnt lgkmcnt(8)
	v_mfma_f32_16x16x32_bf16 v[126:129], v[184:187], v[168:171], v[126:129]
	v_mfma_f32_16x16x32_bf16 v[122:125], v[184:187], v[172:175], v[122:125]
	v_add3_u32 v0, s38, v153, v151
	v_mfma_f32_16x16x32_bf16 v[110:113], v[188:191], v[168:171], v[110:113]
	v_mfma_f32_16x16x32_bf16 v[106:109], v[188:191], v[172:175], v[106:109]
	v_add3_u32 v159, s38, v153, v158
	s_waitcnt lgkmcnt(6)
	v_mfma_f32_16x16x32_bf16 v[94:97], v[192:195], v[168:171], v[94:97]
	v_mfma_f32_16x16x32_bf16 v[90:93], v[192:195], v[172:175], v[90:93]
	v_add3_u32 v209, s38, v152, v167
	v_mfma_f32_16x16x32_bf16 v[78:81], v[196:199], v[168:171], v[78:81]
	v_mfma_f32_16x16x32_bf16 v[74:77], v[196:199], v[172:175], v[74:77]
	v_add3_u32 v240, s38, v152, v165
	s_waitcnt lgkmcnt(4)
	v_mfma_f32_16x16x32_bf16 v[62:65], v[200:203], v[168:171], v[62:65]
	v_mfma_f32_16x16x32_bf16 v[58:61], v[200:203], v[172:175], v[58:61]
	v_add3_u32 v242, s38, v152, v163
	v_mfma_f32_16x16x32_bf16 v[46:49], v[204:207], v[168:171], v[46:49]
	v_mfma_f32_16x16x32_bf16 v[42:45], v[204:207], v[172:175], v[42:45]
	v_add3_u32 v208, s38, v152, v150
	s_waitcnt lgkmcnt(2)
	v_mfma_f32_16x16x32_bf16 v[30:33], v[232:235], v[168:171], v[30:33]
	v_mfma_f32_16x16x32_bf16 v[26:29], v[232:235], v[172:175], v[26:29]
	v_add3_u32 v231, s38, v152, v166
	v_mfma_f32_16x16x32_bf16 v[14:17], v[236:239], v[168:171], v[14:17]
	v_mfma_f32_16x16x32_bf16 v[10:13], v[236:239], v[172:175], v[10:13]
	v_add3_u32 v241, s38, v152, v164
	v_add3_u32 v243, s38, v152, v162
	s_waitcnt vmcnt(0) lgkmcnt(0)
	s_barrier
; template <class Epi>
; DI void gemm8_tile(const bf16_t* __restrict__ Ab, int lda, const bf16_t* __restrict__ Bb, int ldb, int K, int brow, int bcol, const Epi epi,
;                    bool staged, bool has_next, const bf16_t* __restrict__ Abn, const bf16_t* __restrict__ Bbn) {
;     ...
;   for (int t = 0; t < nt; ++t) {
;     const int cur = t & 1;
;     const unsigned char* sa = smem + cur * G8_STAGE_B;
;     const unsigned char* sb = sa + G8_TILE_B;
; #pragma unroll
;     for (int ks = 0; ks < 2; ++ks) {
;       bf16x8 At[8], Bf[4];
;       Bf[0] = *(const bf16x8*)(sb + lds_byte2(wc * 64 + fr, ks * 32 + fq * 8));
;       At[0] = *(const bf16x8*)(sa + lds_byte2(wr * 128 + fr, ks * 32 + fq * 8));
; #pragma unroll
;       for (int n = 1; n < 4; ++n) Bf[n] = *(const bf16x8*)(sb + lds_byte2(wc * 64 + n * 16 + fr, ks * 32 + fq * 8));
; #pragma unroll
;       for (int m = 1; m < 8; ++m) At[m] = *(const bf16x8*)(sa + lds_byte2(wr * 128 + m * 16 + fr, ks * 32 + fq * 8));
;       {
;         __builtin_amdgcn_sched_barrier(0);
;         if (t + 1 < nt) { G8_STAGE_R(cur ^ 1, Ab + (t + 1) * 64, Bb + (t + 1) * 64, 2 * ks, 2 * ks + 2); }
;         else if (has_next) { G8_STAGE_R(0, Abn, Bbn, 2 * ks, 2 * ks + 2); }
;         __builtin_amdgcn_sched_barrier(0);
;       }
	ds_read_b128 v[168:171], v0 offset:32768
	ds_read_b128 v[172:175], v0 offset:34816
	v_mfma_f32_16x16x32_bf16 v[118:121], v[184:187], v[176:179], v[118:121]
	v_mfma_f32_16x16x32_bf16 v[114:117], v[184:187], v[180:183], v[114:117]
	ds_read_b128 v[184:187], v159
	v_mfma_f32_16x16x32_bf16 v[102:105], v[188:191], v[176:179], v[102:105]
	v_mfma_f32_16x16x32_bf16 v[98:101], v[188:191], v[180:183], v[98:101]
	ds_read_b128 v[188:191], v208
	v_mfma_f32_16x16x32_bf16 v[86:89], v[192:195], v[176:179], v[86:89]
	v_mfma_f32_16x16x32_bf16 v[82:85], v[192:195], v[180:183], v[82:85]
	ds_read_b128 v[192:195], v209
	v_mfma_f32_16x16x32_bf16 v[70:73], v[196:199], v[176:179], v[70:73]
	v_mfma_f32_16x16x32_bf16 v[66:69], v[196:199], v[180:183], v[66:69]
	ds_read_b128 v[196:199], v231
	v_mfma_f32_16x16x32_bf16 v[54:57], v[200:203], v[176:179], v[54:57]
	v_mfma_f32_16x16x32_bf16 v[50:53], v[200:203], v[180:183], v[50:53]
	ds_read_b128 v[200:203], v240
	v_mfma_f32_16x16x32_bf16 v[38:41], v[204:207], v[176:179], v[38:41]
	v_mfma_f32_16x16x32_bf16 v[34:37], v[204:207], v[180:183], v[34:37]
	ds_read_b128 v[204:207], v241
	v_mfma_f32_16x16x32_bf16 v[22:25], v[232:235], v[176:179], v[22:25]
	v_mfma_f32_16x16x32_bf16 v[18:21], v[232:235], v[180:183], v[18:21]
	ds_read_b128 v[232:235], v242
	v_mfma_f32_16x16x32_bf16 v[6:9], v[236:239], v[176:179], v[6:9]
	v_mfma_f32_16x16x32_bf16 v[2:5], v[236:239], v[180:183], v[2:5]
	ds_read_b128 v[236:239], v243
	ds_read_b128 v[176:179], v0 offset:36864
	ds_read_b128 v[180:183], v0 offset:38912
	s_add_u32 s0, s0, 0x80
	s_addc_u32 s1, s1, 0
	s_add_i32 s14, s14, 0x10000
	s_cmpk_eq_i32 s0, 0x780
	s_cbranch_scc0 .LBB0_1673
	s_waitcnt lgkmcnt(0)
	s_add_i32 s0, 0, 0x18000
	v_add_u32_e32 v0, s0, v153
	v_add_u32_e32 v0, v0, v151
	v_add_u32_e32 v130, s30, v153
	v_add_u32_e32 v206, v130, v158
	ds_read_b128 v[130:133], v0
	ds_read_b128 v[134:137], v0 offset:2048
	ds_read_b128 v[138:141], v0 offset:4096
	ds_read_b128 v[142:145], v0 offset:6144
	v_add_u32_e32 v170, s30, v152
	v_add_u32_e32 v208, v170, v167
	v_add_u32_e32 v231, v170, v165
	v_add_u32_e32 v233, v170, v163
	v_add_u32_e32 v207, v170, v150
	ds_read_b128 v[150:153], v206
	ds_read_b128 v[158:161], v207
	v_add_u32_e32 v209, v170, v166
	ds_read_b128 v[166:169], v208
	ds_read_b128 v[174:177], v209
	v_add_u32_e32 v232, v170, v164
	ds_read_b128 v[182:185], v231
	ds_read_b128 v[190:193], v232
	v_add_u32_e32 v234, v170, v162
	ds_read_b128 v[198:201], v233
	ds_read_b128 v[202:205], v234
	v_cndmask_b32_e64 v162, 0, 1, s[12:13]
	v_cmp_ne_u32_e64 s[0:1], 1, v162
	s_andn2_b64 vcc, exec, s[12:13]
	s_cbranch_vccnz .LBB0_1676
	v_readfirstlane_b32 s12, v157
	v_lshl_add_u64 v[162:163], s[8:9], 0, v[148:149]
	s_mov_b32 m0, s12
	v_readfirstlane_b32 s12, v156
	v_lshl_add_u64 v[148:149], s[10:11], 0, v[148:149]
	global_load_lds_dwordx4 v[162:163], off
	s_mov_b32 m0, s12
	v_readfirstlane_b32 s12, v155
	v_lshl_add_u64 v[164:165], s[8:9], 0, v[146:147]
	global_load_lds_dwordx4 v[148:149], off
	s_mov_b32 m0, s12
	v_readfirstlane_b32 s12, v154
	v_lshl_add_u64 v[146:147], s[10:11], 0, v[146:147]
	global_load_lds_dwordx4 v[164:165], off
	s_mov_b32 m0, s12
	s_nop 0
	global_load_lds_dwordx4 v[146:147], off

; #define MFMA16(a, b, c) __builtin_amdgcn_mfma_f32_16x16x32_bf16((a), (b), (c), 0, 0, 0)
; template <class Epi>
; DI void gemm8_tile(const bf16_t* __restrict__ Ab, int lda, const bf16_t* __restrict__ Bb, int ldb, int K, int brow, int bcol, const Epi epi,
;                    bool staged, bool has_next, const bf16_t* __restrict__ Abn, const bf16_t* __restrict__ Bbn) {
;     ...
;   for (int t = 0; t < nt; ++t) {
;     const int cur = t & 1;
;     const unsigned char* sa = smem + cur * G8_STAGE_B;
;     const unsigned char* sb = sa + G8_TILE_B;
; #pragma unroll
;     for (int ks = 0; ks < 2; ++ks) {
;       bf16x8 At[8], Bf[4];
;       Bf[0] = *(const bf16x8*)(sb + lds_byte2(wc * 64 + fr, ks * 32 + fq * 8));
;       At[0] = *(const bf16x8*)(sa + lds_byte2(wr * 128 + fr, ks * 32 + fq * 8));
; #pragma unroll
;       for (int n = 1; n < 4; ++n) Bf[n] = *(const bf16x8*)(sb + lds_byte2(wc * 64 + n * 16 + fr, ks * 32 + fq * 8));
; #pragma unroll
;       for (int m = 1; m < 8; ++m) At[m] = *(const bf16x8*)(sa + lds_byte2(wr * 128 + m * 16 + fr, ks * 32 + fq * 8));
;       {
;         __builtin_amdgcn_sched_barrier(0);
;         if (t + 1 < nt) { G8_STAGE_R(cur ^ 1, Ab + (t + 1) * 64, Bb + (t + 1) * 64, 2 * ks, 2 * ks + 2); }
;         else if (has_next) { G8_STAGE_R(0, Abn, Bbn, 2 * ks, 2 * ks + 2); }
;         __builtin_amdgcn_sched_barrier(0);
;       }
; #pragma unroll
;       for (int m = 0; m < 8; ++m)
; #pragma unroll
;         for (int n = 0; n < 4; ++n) acc[m][n] = MFMA16(At[m], Bf[n], acc[m][n]);
;       __builtin_amdgcn_sched_barrier(0);
;     }
;     asm volatile("s_waitcnt vmcnt(0)" ::: "memory");
;     __syncthreads();
.LBB0_1695:
	s_and_b32 s59, s58, 0x10000
	s_xor_b32 s70, s59, 0x10000
	v_add_u32_e32 v244, s70, v185
	s_nop 0
	v_readfirstlane_b32 s59, v244
	s_waitcnt lgkmcnt(8)
	v_mfma_f32_16x16x32_bf16 v[126:129], v[174:177], v[158:161], v[126:129]
	v_mfma_f32_16x16x32_bf16 v[122:125], v[174:177], v[162:165], v[122:125]
	s_mov_b32 m0, s59
	v_lshl_add_u64 v[208:209], v[130:131], 0, s[0:1]
	global_load_lds_dwordx4 v[208:209], off
	v_mfma_f32_16x16x32_bf16 v[110:113], v[186:189], v[158:161], v[110:113]
	v_mfma_f32_16x16x32_bf16 v[106:109], v[186:189], v[162:165], v[106:109]
	s_add_u32 m0, s59, 0x8000
	v_lshl_add_u64 v[208:209], v[138:139], 0, s[0:1]
	global_load_lds_dwordx4 v[208:209], off
	s_waitcnt lgkmcnt(6)
	v_mfma_f32_16x16x32_bf16 v[94:97], v[190:193], v[158:161], v[94:97]
	v_mfma_f32_16x16x32_bf16 v[90:93], v[190:193], v[162:165], v[90:93]
	s_add_u32 m0, s59, 0x2000
	v_lshl_add_u64 v[208:209], v[132:133], 0, s[0:1]
	global_load_lds_dwordx4 v[208:209], off
	v_mfma_f32_16x16x32_bf16 v[78:81], v[212:215], v[158:161], v[78:81]
	v_mfma_f32_16x16x32_bf16 v[74:77], v[212:215], v[162:165], v[74:77]
	s_add_u32 m0, s59, 0xa000
	v_lshl_add_u64 v[208:209], v[140:141], 0, s[0:1]
	global_load_lds_dwordx4 v[208:209], off
	s_waitcnt lgkmcnt(4)
	v_mfma_f32_16x16x32_bf16 v[62:65], v[222:225], v[158:161], v[62:65]
	v_mfma_f32_16x16x32_bf16 v[58:61], v[222:225], v[162:165], v[58:61]
	s_add_u32 m0, s59, 0x4000
	v_lshl_add_u64 v[208:209], v[134:135], 0, s[0:1]
	global_load_lds_dwordx4 v[208:209], off
	v_mfma_f32_16x16x32_bf16 v[46:49], v[226:229], v[158:161], v[46:49]
	v_mfma_f32_16x16x32_bf16 v[42:45], v[226:229], v[162:165], v[42:45]
	s_add_u32 m0, s59, 0xc000
	v_lshl_add_u64 v[208:209], v[142:143], 0, s[0:1]
	global_load_lds_dwordx4 v[208:209], off
	s_waitcnt lgkmcnt(2)
	v_mfma_f32_16x16x32_bf16 v[30:33], v[230:233], v[158:161], v[30:33]
	v_mfma_f32_16x16x32_bf16 v[26:29], v[230:233], v[162:165], v[26:29]
	s_add_u32 m0, s59, 0x6000
	v_lshl_add_u64 v[208:209], v[136:137], 0, s[0:1]
	global_load_lds_dwordx4 v[208:209], off
	v_mfma_f32_16x16x32_bf16 v[14:17], v[234:237], v[158:161], v[14:17]
	v_mfma_f32_16x16x32_bf16 v[10:13], v[234:237], v[162:165], v[10:13]
	s_add_u32 m0, s59, 0xe000
	v_lshl_add_u64 v[208:209], v[144:145], 0, s[0:1]
	global_load_lds_dwordx4 v[208:209], off
	ds_read_b128 v[158:161], v0 offset:33792
	ds_read_b128 v[162:165], v0 offset:35840
	s_waitcnt lgkmcnt(2)
	v_mfma_f32_16x16x32_bf16 v[118:121], v[174:177], v[166:169], v[118:121]
	v_mfma_f32_16x16x32_bf16 v[114:117], v[174:177], v[170:173], v[114:117]
	ds_read_b128 v[174:177], v157 offset:1024
	v_mfma_f32_16x16x32_bf16 v[102:105], v[186:189], v[166:169], v[102:105]
	v_mfma_f32_16x16x32_bf16 v[98:101], v[186:189], v[170:173], v[98:101]
	ds_read_b128 v[186:189], v207 offset:1024
	v_mfma_f32_16x16x32_bf16 v[86:89], v[190:193], v[166:169], v[86:89]
	v_mfma_f32_16x16x32_bf16 v[82:85], v[190:193], v[170:173], v[82:85]
	ds_read_b128 v[190:193], v238 offset:1024
	v_mfma_f32_16x16x32_bf16 v[70:73], v[212:215], v[166:169], v[70:73]
	v_mfma_f32_16x16x32_bf16 v[66:69], v[212:215], v[170:173], v[66:69]
	ds_read_b128 v[212:215], v239 offset:1024
	v_mfma_f32_16x16x32_bf16 v[54:57], v[222:225], v[166:169], v[54:57]
	v_mfma_f32_16x16x32_bf16 v[50:53], v[222:225], v[170:173], v[50:53]
	ds_read_b128 v[222:225], v240 offset:1024
	v_mfma_f32_16x16x32_bf16 v[38:41], v[226:229], v[166:169], v[38:41]
	v_mfma_f32_16x16x32_bf16 v[34:37], v[226:229], v[170:173], v[34:37]
	ds_read_b128 v[226:229], v241 offset:1024
	v_mfma_f32_16x16x32_bf16 v[22:25], v[230:233], v[166:169], v[22:25]
	v_mfma_f32_16x16x32_bf16 v[18:21], v[230:233], v[170:173], v[18:21]
	ds_read_b128 v[230:233], v242 offset:1024
	v_mfma_f32_16x16x32_bf16 v[6:9], v[234:237], v[166:169], v[6:9]
	v_mfma_f32_16x16x32_bf16 v[2:5], v[234:237], v[170:173], v[2:5]
	ds_read_b128 v[234:237], v243 offset:1024
	ds_read_b128 v[166:169], v0 offset:37888
	ds_read_b128 v[170:173], v0 offset:39936
	s_waitcnt lgkmcnt(8)
	v_mfma_f32_16x16x32_bf16 v[126:129], v[174:177], v[158:161], v[126:129]
	v_mfma_f32_16x16x32_bf16 v[122:125], v[174:177], v[162:165], v[122:125]
	v_add3_u32 v0, s70, v155, v153
	v_mfma_f32_16x16x32_bf16 v[110:113], v[186:189], v[158:161], v[110:113]
	v_mfma_f32_16x16x32_bf16 v[106:109], v[186:189], v[162:165], v[106:109]
	v_add3_u32 v157, s70, v155, v156
	s_waitcnt lgkmcnt(6)
	v_mfma_f32_16x16x32_bf16 v[94:97], v[190:193], v[158:161], v[94:97]
	v_mfma_f32_16x16x32_bf16 v[90:93], v[190:193], v[162:165], v[90:93]
	v_add3_u32 v238, s70, v154, v152
	v_mfma_f32_16x16x32_bf16 v[78:81], v[212:215], v[158:161], v[78:81]
	v_mfma_f32_16x16x32_bf16 v[74:77], v[212:215], v[162:165], v[74:77]
	v_add3_u32 v240, s70, v154, v149
	s_waitcnt lgkmcnt(4)
	v_mfma_f32_16x16x32_bf16 v[62:65], v[222:225], v[158:161], v[62:65]
	v_mfma_f32_16x16x32_bf16 v[58:61], v[222:225], v[162:165], v[58:61]
	v_add3_u32 v242, s70, v154, v147
	v_mfma_f32_16x16x32_bf16 v[46:49], v[226:229], v[158:161], v[46:49]
	v_mfma_f32_16x16x32_bf16 v[42:45], v[226:229], v[162:165], v[42:45]
	v_add3_u32 v207, s70, v154, v150
	s_waitcnt lgkmcnt(2)
	v_mfma_f32_16x16x32_bf16 v[30:33], v[230:233], v[158:161], v[30:33]
	v_mfma_f32_16x16x32_bf16 v[26:29], v[230:233], v[162:165], v[26:29]
	v_add3_u32 v239, s70, v154, v151
	v_mfma_f32_16x16x32_bf16 v[14:17], v[234:237], v[158:161], v[14:17]
	v_mfma_f32_16x16x32_bf16 v[10:13], v[234:237], v[162:165], v[10:13]
	v_add3_u32 v241, s70, v154, v148
	v_add3_u32 v243, s70, v154, v146
	s_waitcnt vmcnt(0) lgkmcnt(0)
	s_barrier
; template <class Epi>
; DI void gemm8_tile(const bf16_t* __restrict__ Ab, int lda, const bf16_t* __restrict__ Bb, int ldb, int K, int brow, int bcol, const Epi epi,
;                    bool staged, bool has_next, const bf16_t* __restrict__ Abn, const bf16_t* __restrict__ Bbn) {
;     ...
;   for (int t = 0; t < nt; ++t) {
;     const int cur = t & 1;
;     const unsigned char* sa = smem + cur * G8_STAGE_B;
;     const unsigned char* sb = sa + G8_TILE_B;
; #pragma unroll
;     for (int ks = 0; ks < 2; ++ks) {
;       bf16x8 At[8], Bf[4];
;       Bf[0] = *(const bf16x8*)(sb + lds_byte2(wc * 64 + fr, ks * 32 + fq * 8));
;       At[0] = *(const bf16x8*)(sa + lds_byte2(wr * 128 + fr, ks * 32 + fq * 8));
; #pragma unroll
;       for (int n = 1; n < 4; ++n) Bf[n] = *(const bf16x8*)(sb + lds_byte2(wc * 64 + n * 16 + fr, ks * 32 + fq * 8));
; #pragma unroll
;       for (int m = 1; m < 8; ++m) At[m] = *(const bf16x8*)(sa + lds_byte2(wr * 128 + m * 16 + fr, ks * 32 + fq * 8));
;       {
;         __builtin_amdgcn_sched_barrier(0);
;         if (t + 1 < nt) { G8_STAGE_R(cur ^ 1, Ab + (t + 1) * 64, Bb + (t + 1) * 64, 2 * ks, 2 * ks + 2); }
;         else if (has_next) { G8_STAGE_R(0, Abn, Bbn, 2 * ks, 2 * ks + 2); }
;         __builtin_amdgcn_sched_barrier(0);
;       }
	ds_read_b128 v[158:161], v0 offset:32768
	ds_read_b128 v[162:165], v0 offset:34816
	v_mfma_f32_16x16x32_bf16 v[118:121], v[174:177], v[166:169], v[118:121]
	v_mfma_f32_16x16x32_bf16 v[114:117], v[174:177], v[170:173], v[114:117]
	ds_read_b128 v[174:177], v157
	v_mfma_f32_16x16x32_bf16 v[102:105], v[186:189], v[166:169], v[102:105]
	v_mfma_f32_16x16x32_bf16 v[98:101], v[186:189], v[170:173], v[98:101]
	ds_read_b128 v[186:189], v207
	v_mfma_f32_16x16x32_bf16 v[86:89], v[190:193], v[166:169], v[86:89]
	v_mfma_f32_16x16x32_bf16 v[82:85], v[190:193], v[170:173], v[82:85]
	ds_read_b128 v[190:193], v238
	v_mfma_f32_16x16x32_bf16 v[70:73], v[212:215], v[166:169], v[70:73]
	v_mfma_f32_16x16x32_bf16 v[66:69], v[212:215], v[170:173], v[66:69]
	ds_read_b128 v[212:215], v239
	v_mfma_f32_16x16x32_bf16 v[54:57], v[222:225], v[166:169], v[54:57]
	v_mfma_f32_16x16x32_bf16 v[50:53], v[222:225], v[170:173], v[50:53]
	ds_read_b128 v[222:225], v240
	v_mfma_f32_16x16x32_bf16 v[38:41], v[226:229], v[166:169], v[38:41]
	v_mfma_f32_16x16x32_bf16 v[34:37], v[226:229], v[170:173], v[34:37]
	ds_read_b128 v[226:229], v241
	v_mfma_f32_16x16x32_bf16 v[22:25], v[230:233], v[166:169], v[22:25]
	v_mfma_f32_16x16x32_bf16 v[18:21], v[230:233], v[170:173], v[18:21]
	ds_read_b128 v[230:233], v242
	v_mfma_f32_16x16x32_bf16 v[6:9], v[234:237], v[166:169], v[6:9]
	v_mfma_f32_16x16x32_bf16 v[2:5], v[234:237], v[170:173], v[2:5]
	ds_read_b128 v[234:237], v243
	ds_read_b128 v[166:169], v0 offset:36864
	ds_read_b128 v[170:173], v0 offset:38912
	s_add_u32 s0, s0, 0x80
	s_addc_u32 s1, s1, 0
	s_add_i32 s58, s58, 0x10000
	s_cmpk_eq_i32 s0, 0x1580
	s_cbranch_scc0 .LBB0_1695
	s_waitcnt lgkmcnt(0)
	s_add_i32 s0, 0, 0x18000
	v_add_u32_e32 v0, s0, v155
	v_add_u32_e32 v0, v0, v153
	v_add_u32_e32 v130, s30, v155
	v_add_u32_e32 v190, v130, v156
	ds_read_b128 v[130:133], v0
	ds_read_b128 v[134:137], v0 offset:2048
	ds_read_b128 v[138:141], v0 offset:4096
	ds_read_b128 v[142:145], v0 offset:6144
	v_add_u32_e32 v174, s30, v154
	v_add_u32_e32 v192, v174, v152
	v_add_u32_e32 v207, v174, v149
	v_add_u32_e32 v209, v174, v147
	v_add_u32_e32 v191, v174, v150
	ds_read_b128 v[170:173], v190
	ds_read_b128 v[162:165], v191
	v_add_u32_e32 v193, v174, v151
	ds_read_b128 v[166:169], v192
	ds_read_b128 v[154:157], v193
	v_add_u32_e32 v208, v174, v148
	ds_read_b128 v[158:161], v207
	ds_read_b128 v[150:153], v208
	v_add_u32_e32 v212, v174, v146
	ds_read_b128 v[174:177], v209
	ds_read_b128 v[146:149], v212
	v_cndmask_b32_e64 v186, 0, 1, s[14:15]
	v_cmp_ne_u32_e64 s[0:1], 1, v186
	s_andn2_b64 vcc, exec, s[14:15]
	s_cbranch_vccnz .LBB0_1698
	v_readfirstlane_b32 s14, v185
	v_lshl_add_u64 v[188:189], s[6:7], 0, v[178:179]
	v_lshl_add_u64 v[178:179], s[4:5], 0, v[178:179]
	s_mov_b32 m0, s14
	v_readfirstlane_b32 s14, v184
	global_load_lds_dwordx4 v[178:179], off
	s_mov_b32 m0, s14
	v_readfirstlane_b32 s14, v183
	v_lshl_add_u64 v[186:187], s[6:7], 0, v[180:181]
	v_lshl_add_u64 v[180:181], s[4:5], 0, v[180:181]
	global_load_lds_dwordx4 v[188:189], off
	s_mov_b32 m0, s14
	v_readfirstlane_b32 s14, v182
	global_load_lds_dwordx4 v[180:181], off
	s_mov_b32 m0, s14
	s_nop 0
	global_load_lds_dwordx4 v[186:187], off
